# all K-loop MFMA blocks re-ordered into back-to-back accumulate chains (dependence-safe), plus load segments without VALU copies
# speedup vs baseline: 1.0220x; 1.0113x over previous
; #define PG8_STAGE(bufoff, gbase, voff) do { const char* gb_ = (const char*)(gbase); asm volatile("" : "+s"(gb_)); _Pragma("unroll") for (int _i = 0; _i < 2; ++_i) { unsigned vo_ = (voff)[_i]; asm volatile("" : "+v"(vo_));        \
;         __builtin_amdgcn_global_load_lds((const unsigned*)(gb_ + vo_), (PG8_LAS unsigned*)(lds + (bufoff) + ldsw + _i * 8192), 16, 0, 0); } } while (0)
; #define PG8_LDA(dst, b, h) do { _Pragma("unroll") for (int m = 0; m < 4; ++m) _Pragma("unroll") for (int k = 0; k < 2; ++k) dst[m][k] = *(const PG8_LAS bf16x8*)(lds + PG8_SA(b, h) + aoff + m * 2048 + k * 1024); } while (0)
; #define PG8_LDB(dst, b, h) do { _Pragma("unroll") for (int n = 0; n < 2; ++n) _Pragma("unroll") for (int k = 0; k < 2; ++k) dst[n][k] = *(const PG8_LAS bf16x8*)(lds + PG8_SB(b, h) + boff + n * 2048 + k * 1024); } while (0)
; #define PG8_MMA(ai, bj, At, Bt) do { __builtin_amdgcn_s_setprio(1); _Pragma("unroll") for (int m = 0; m < 4; ++m) _Pragma("unroll") for (int n = 0; n < 2; ++n) _Pragma("unroll") for (int k = 0; k < 2; ++k) \
;         acc[ai][bj][m][n] = __builtin_amdgcn_mfma_f32_16x16x32_bf16(Bt[n][k], At[m][k], acc[ai][bj][m][n], 0, 0, 0); __builtin_amdgcn_s_setprio(0); } while (0)
; #define PG8_WAIT_V(n) asm volatile("s_waitcnt vmcnt(" #n ")" ::: "memory")
; template <class Epi, class Sched, bool ALIGN_EPI = false, bool SP2 = false>
; __device__ __forceinline__ void gemm_phase(PG8_LAS unsigned char* lds, const Gemm g, const Sched& S, const Epi& E) {
;     ...
;             const bool last = (t == nt - 2);
;             const char* a1 = cA + (size_t)(t + 1) * kstep;
;             const char* a2 = last ? nA : cA + (size_t)(t + 2) * kstep; const char* b2 = last ? nB : cB + (size_t)(t + 2) * kstep;
;             const char* a3 = a2 + kstep; const char* b3 = b2 + kstep;
;             if (last && has_next) S.a_ready(nxt);
;             if constexpr (SP2) {
;             PG8_LDB(B0, 0, 0); PG8_LDB(B1, 0, 1); PG8_SCHED; PG8_LDA(At, 0, 0); PG8_STAGE(PG8_SA(1, 1), a1 + hstep, voffA);
;             PG8_WAIT_V(8); PG8_WAIT_L(0); PG8_BAR; PG8_MMA(0, 0, At, B0); PG8_MMA(0, 1, At, B1); PG8_BAR; PG8_SCHED;
;             PG8_LDA(At, 0, 1); PG8_STAGE(PG8_SB(0, 0), b2, voffB); PG8_STAGE(PG8_SB(0, 1), b2 + hstep, voffB); PG8_STAGE(PG8_SA(0, 0), a2, voffA);
;             PG8_WAIT_V(8); PG8_WAIT_L(0); PG8_BAR; PG8_MMA(1, 0, At, B0); PG8_MMA(1, 1, At, B1); PG8_BAR; PG8_SCHED;
.LBB0_232:
	s_add_u32 s2, s0, 0x100
	s_addc_u32 s3, s1, 0
	s_cmp_eq_u32 s30, 28
	s_cselect_b32 s10, s25, s2
	s_cselect_b32 s11, s24, s3
	s_cselect_b32 s8, s27, s28
	s_cselect_b32 s9, s26, s29
	s_add_u32 s6, s10, 0x80
	s_addc_u32 s7, s11, 0
	s_add_i32 s31, 0, 0x10000
	s_add_i32 s33, 0, 0x14000
	ds_read_b128 v[66:69], v244
	ds_read_b128 v[70:73], v244 offset:1024
	ds_read_b128 v[74:77], v244 offset:2048
	ds_read_b128 v[78:81], v244 offset:3072
	ds_read_b128 v[146:149], v244 offset:16384
	ds_read_b128 v[150:153], v244 offset:17408
	ds_read_b128 v[154:157], v244 offset:18432
	ds_read_b128 v[158:161], v244 offset:19456
	s_add_u32 s0, s0, 0x80080
	s_addc_u32 s1, s1, 0
	ds_read_b128 v[178:181], v223
	ds_read_b128 v[182:185], v223 offset:1024
	ds_read_b128 v[192:195], v223 offset:2048
	ds_read_b128 v[196:199], v223 offset:3072
	ds_read_b128 v[200:203], v223 offset:4096
	ds_read_b128 v[204:207], v223 offset:5120
	ds_read_b128 v[208:211], v223 offset:6144
	ds_read_b128 v[212:215], v223 offset:7168
	s_add_i32 m0, s13, 0xc000
	s_nop 0
	global_load_lds_dwordx4 v1, s[0:1]
	s_add_i32 m0, s13, 0xe000
	s_nop 0
	global_load_lds_dwordx4 v191, s[0:1]
	s_waitcnt vmcnt(8)
	s_waitcnt lgkmcnt(0)
	s_barrier
	s_setprio 1
	s_waitcnt lgkmcnt(0)
	v_mfma_f32_16x16x32_bf16 v[142:145], v[66:69], v[178:181], v[142:145]
	v_mfma_f32_16x16x32_bf16 v[142:145], v[70:73], v[182:185], v[142:145]
	v_mfma_f32_16x16x32_bf16 v[134:137], v[66:69], v[192:195], v[134:137]
	v_mfma_f32_16x16x32_bf16 v[134:137], v[70:73], v[196:199], v[134:137]
	v_mfma_f32_16x16x32_bf16 v[126:129], v[66:69], v[200:203], v[126:129]
	v_mfma_f32_16x16x32_bf16 v[126:129], v[70:73], v[204:207], v[126:129]
	v_mfma_f32_16x16x32_bf16 v[118:121], v[66:69], v[208:211], v[118:121]
	v_mfma_f32_16x16x32_bf16 v[118:121], v[70:73], v[212:215], v[118:121]
	v_mfma_f32_16x16x32_bf16 v[138:141], v[74:77], v[178:181], v[138:141]
	v_mfma_f32_16x16x32_bf16 v[138:141], v[78:81], v[182:185], v[138:141]
	v_mfma_f32_16x16x32_bf16 v[130:133], v[74:77], v[192:195], v[130:133]
	v_mfma_f32_16x16x32_bf16 v[130:133], v[78:81], v[196:199], v[130:133]
	v_mfma_f32_16x16x32_bf16 v[122:125], v[74:77], v[200:203], v[122:125]
	v_mfma_f32_16x16x32_bf16 v[122:125], v[78:81], v[204:207], v[122:125]
	v_mfma_f32_16x16x32_bf16 v[114:117], v[74:77], v[208:211], v[114:117]
	v_mfma_f32_16x16x32_bf16 v[114:117], v[78:81], v[212:215], v[114:117]
	s_setprio 0
	s_setprio 1
	v_mfma_f32_16x16x32_bf16 v[62:65], v[146:149], v[178:181], v[62:65]
	v_mfma_f32_16x16x32_bf16 v[62:65], v[150:153], v[182:185], v[62:65]
	v_mfma_f32_16x16x32_bf16 v[54:57], v[146:149], v[192:195], v[54:57]
	v_mfma_f32_16x16x32_bf16 v[54:57], v[150:153], v[196:199], v[54:57]
	v_mfma_f32_16x16x32_bf16 v[46:49], v[146:149], v[200:203], v[46:49]
	v_mfma_f32_16x16x32_bf16 v[46:49], v[150:153], v[204:207], v[46:49]
	v_mfma_f32_16x16x32_bf16 v[38:41], v[146:149], v[208:211], v[38:41]
	v_mfma_f32_16x16x32_bf16 v[38:41], v[150:153], v[212:215], v[38:41]
	v_mfma_f32_16x16x32_bf16 v[58:61], v[154:157], v[178:181], v[58:61]
	v_mfma_f32_16x16x32_bf16 v[58:61], v[158:161], v[182:185], v[58:61]
	v_mfma_f32_16x16x32_bf16 v[50:53], v[154:157], v[192:195], v[50:53]
	v_mfma_f32_16x16x32_bf16 v[50:53], v[158:161], v[196:199], v[50:53]
	v_mfma_f32_16x16x32_bf16 v[42:45], v[154:157], v[200:203], v[42:45]
	v_mfma_f32_16x16x32_bf16 v[42:45], v[158:161], v[204:207], v[42:45]
	v_mfma_f32_16x16x32_bf16 v[34:37], v[154:157], v[208:211], v[34:37]
	v_mfma_f32_16x16x32_bf16 v[34:37], v[158:161], v[212:215], v[34:37]
	s_setprio 0
	s_barrier
	s_mov_b64 s[0:1], s[8:9]
	s_add_i32 s31, s31, s12
	ds_read_b128 v[178:181], v223 offset:16384
	ds_read_b128 v[182:185], v223 offset:17408
	ds_read_b128 v[192:195], v223 offset:18432
	ds_read_b128 v[196:199], v223 offset:19456
	ds_read_b128 v[200:203], v223 offset:20480
	ds_read_b128 v[204:207], v223 offset:21504
	ds_read_b128 v[208:211], v223 offset:22528
	ds_read_b128 v[212:215], v223 offset:23552
	s_mov_b32 m0, s31
	s_nop 0
	global_load_lds_dwordx4 v189, s[0:1]
	s_add_i32 m0, s31, 0x2000
	s_nop 0
	global_load_lds_dwordx4 v219, s[0:1]
	s_add_u32 s0, s8, 0x80000
	s_addc_u32 s1, s9, 0
	s_add_i32 s31, s33, s12
	s_mov_b32 m0, s31
	s_nop 0
	global_load_lds_dwordx4 v189, s[0:1]
	s_add_i32 m0, s31, 0x2000
	s_nop 0
	global_load_lds_dwordx4 v219, s[0:1]
	s_mov_b64 s[0:1], s[10:11]
	s_mov_b32 m0, s13
	s_nop 0
	global_load_lds_dwordx4 v1, s[0:1]
	s_mov_b32 m0, s14
	s_nop 0
	global_load_lds_dwordx4 v191, s[0:1]
	s_waitcnt vmcnt(8)
	s_waitcnt lgkmcnt(0)
	s_barrier
	s_setprio 1
	s_waitcnt lgkmcnt(0)
	v_mfma_f32_16x16x32_bf16 v[110:113], v[66:69], v[178:181], v[110:113]
	v_mfma_f32_16x16x32_bf16 v[110:113], v[70:73], v[182:185], v[110:113]
	v_mfma_f32_16x16x32_bf16 v[102:105], v[66:69], v[192:195], v[102:105]
	v_mfma_f32_16x16x32_bf16 v[102:105], v[70:73], v[196:199], v[102:105]
	v_mfma_f32_16x16x32_bf16 v[94:97], v[66:69], v[200:203], v[94:97]
	v_mfma_f32_16x16x32_bf16 v[94:97], v[70:73], v[204:207], v[94:97]
	v_mfma_f32_16x16x32_bf16 v[66:69], v[66:69], v[208:211], v[86:89]
	v_mfma_f32_16x16x32_bf16 v[66:69], v[70:73], v[212:215], v[66:69]
	v_mfma_f32_16x16x32_bf16 v[106:109], v[74:77], v[178:181], v[106:109]
	v_mfma_f32_16x16x32_bf16 v[106:109], v[78:81], v[182:185], v[106:109]
	v_mfma_f32_16x16x32_bf16 v[98:101], v[74:77], v[192:195], v[98:101]
	v_mfma_f32_16x16x32_bf16 v[98:101], v[78:81], v[196:199], v[98:101]
	v_mfma_f32_16x16x32_bf16 v[90:93], v[74:77], v[200:203], v[90:93]
	v_mfma_f32_16x16x32_bf16 v[90:93], v[78:81], v[204:207], v[90:93]
	v_mfma_f32_16x16x32_bf16 v[70:73], v[74:77], v[208:211], v[82:85]
	v_mfma_f32_16x16x32_bf16 v[70:73], v[78:81], v[212:215], v[70:73]
	s_setprio 0
	s_setprio 1
	v_mfma_f32_16x16x32_bf16 v[30:33], v[146:149], v[178:181], v[30:33]
	v_mfma_f32_16x16x32_bf16 v[30:33], v[150:153], v[182:185], v[30:33]
	v_mfma_f32_16x16x32_bf16 v[22:25], v[146:149], v[192:195], v[22:25]
	v_mfma_f32_16x16x32_bf16 v[22:25], v[150:153], v[196:199], v[22:25]
	v_mfma_f32_16x16x32_bf16 v[14:17], v[146:149], v[200:203], v[14:17]
	v_mfma_f32_16x16x32_bf16 v[14:17], v[150:153], v[204:207], v[14:17]
	v_mfma_f32_16x16x32_bf16 v[6:9], v[146:149], v[208:211], v[6:9]
	v_mfma_f32_16x16x32_bf16 v[6:9], v[150:153], v[212:215], v[6:9]
	v_mfma_f32_16x16x32_bf16 v[26:29], v[154:157], v[178:181], v[26:29]
	v_mfma_f32_16x16x32_bf16 v[26:29], v[158:161], v[182:185], v[26:29]
	v_mfma_f32_16x16x32_bf16 v[18:21], v[154:157], v[192:195], v[18:21]
	v_mfma_f32_16x16x32_bf16 v[18:21], v[158:161], v[196:199], v[18:21]
	v_mfma_f32_16x16x32_bf16 v[10:13], v[154:157], v[200:203], v[10:13]
	v_mfma_f32_16x16x32_bf16 v[10:13], v[158:161], v[204:207], v[10:13]
	v_mfma_f32_16x16x32_bf16 v[2:5], v[154:157], v[208:211], v[2:5]
	v_mfma_f32_16x16x32_bf16 v[2:5], v[158:161], v[212:215], v[2:5]
	s_setprio 0
	s_barrier
; #define PG8_STAGE(bufoff, gbase, voff) do { const char* gb_ = (const char*)(gbase); asm volatile("" : "+s"(gb_)); _Pragma("unroll") for (int _i = 0; _i < 2; ++_i) { unsigned vo_ = (voff)[_i]; asm volatile("" : "+v"(vo_));        \
;         __builtin_amdgcn_global_load_lds((const unsigned*)(gb_ + vo_), (PG8_LAS unsigned*)(lds + (bufoff) + ldsw + _i * 8192), 16, 0, 0); } } while (0)
; #define PG8_LDA(dst, b, h) do { _Pragma("unroll") for (int m = 0; m < 4; ++m) _Pragma("unroll") for (int k = 0; k < 2; ++k) dst[m][k] = *(const PG8_LAS bf16x8*)(lds + PG8_SA(b, h) + aoff + m * 2048 + k * 1024); } while (0)
; #define PG8_LDB(dst, b, h) do { _Pragma("unroll") for (int n = 0; n < 2; ++n) _Pragma("unroll") for (int k = 0; k < 2; ++k) dst[n][k] = *(const PG8_LAS bf16x8*)(lds + PG8_SB(b, h) + boff + n * 2048 + k * 1024); } while (0)
; #define PG8_MMA(ai, bj, At, Bt) do { __builtin_amdgcn_s_setprio(1); _Pragma("unroll") for (int m = 0; m < 4; ++m) _Pragma("unroll") for (int n = 0; n < 2; ++n) _Pragma("unroll") for (int k = 0; k < 2; ++k) \
;         acc[ai][bj][m][n] = __builtin_amdgcn_mfma_f32_16x16x32_bf16(Bt[n][k], At[m][k], acc[ai][bj][m][n], 0, 0, 0); __builtin_amdgcn_s_setprio(0); } while (0)
; #define PG8_WAIT_V(n) asm volatile("s_waitcnt vmcnt(" #n ")" ::: "memory")
; #define PG8_WAIT_L(n) asm volatile("s_waitcnt lgkmcnt(" #n ")" ::: "memory")
; #define PG8_BAR __builtin_amdgcn_s_barrier()
; #define PG8_SCHED __builtin_amdgcn_sched_barrier(0)
; template <class Epi, class Sched, bool ALIGN_EPI = false, bool SP2 = false>
; __device__ __forceinline__ void gemm_phase(PG8_LAS unsigned char* lds, const Gemm g, const Sched& S, const Epi& E) {
;     ...
;             PG8_LDB(B0, 1, 0); PG8_LDB(B1, 1, 1); PG8_SCHED; PG8_LDA(At, 1, 0); PG8_STAGE(PG8_SA(0, 1), a2 + hstep, voffA);
;             PG8_WAIT_V(8); PG8_WAIT_L(0); PG8_BAR; PG8_MMA(0, 0, At, B0); PG8_MMA(0, 1, At, B1); PG8_BAR; PG8_SCHED;
;             PG8_LDA(At, 1, 1); PG8_STAGE(PG8_SB(1, 0), b3, voffB); PG8_STAGE(PG8_SB(1, 1), b3 + hstep, voffB); PG8_STAGE(PG8_SA(1, 0), a3, voffA);
;             PG8_WAIT_V(8); PG8_WAIT_L(0); PG8_BAR; PG8_MMA(1, 0, At, B0); PG8_MMA(1, 1, At, B1); PG8_BAR; PG8_SCHED;
;     ...
;         if constexpr (ALIGN_EPI) { if (wr == 0) PG8_BAR; }
	s_add_i32 s31, 0, 0x18000
	s_add_i32 s33, 0, 0x1c000
	ds_read_b128 v[74:77], v244 offset:32768
	ds_read_b128 v[78:81], v244 offset:33792
	ds_read_b128 v[82:85], v244 offset:34816
	ds_read_b128 v[146:149], v244 offset:35840
	ds_read_b128 v[150:153], v244 offset:49152
	ds_read_b128 v[154:157], v244 offset:50176
	ds_read_b128 v[158:161], v244 offset:51200
	ds_read_b128 v[178:181], v244 offset:52224
	s_add_u32 s0, s10, 0x80000
	s_addc_u32 s1, s11, 0
	s_mov_b32 m0, s15
	ds_read_b128 v[86:89], v223 offset:32768
	ds_read_b128 v[182:185], v223 offset:33792
	ds_read_b128 v[192:195], v223 offset:34816
	ds_read_b128 v[196:199], v223 offset:35840
	ds_read_b128 v[200:203], v223 offset:36864
	ds_read_b128 v[204:207], v223 offset:37888
	ds_read_b128 v[208:211], v223 offset:38912
	ds_read_b128 v[212:215], v223 offset:39936
	s_nop 0
	global_load_lds_dwordx4 v1, s[0:1]
	s_mov_b32 m0, s16
	s_nop 0
	global_load_lds_dwordx4 v191, s[0:1]
	s_waitcnt vmcnt(8)
	s_waitcnt lgkmcnt(0)
	s_barrier
	s_setprio 1
	s_waitcnt lgkmcnt(0)
	v_mfma_f32_16x16x32_bf16 v[142:145], v[74:77], v[86:89], v[142:145]
	v_mfma_f32_16x16x32_bf16 v[142:145], v[78:81], v[182:185], v[142:145]
	v_mfma_f32_16x16x32_bf16 v[134:137], v[74:77], v[192:195], v[134:137]
	v_mfma_f32_16x16x32_bf16 v[134:137], v[78:81], v[196:199], v[134:137]
	v_mfma_f32_16x16x32_bf16 v[126:129], v[74:77], v[200:203], v[126:129]
	v_mfma_f32_16x16x32_bf16 v[126:129], v[78:81], v[204:207], v[126:129]
	v_mfma_f32_16x16x32_bf16 v[118:121], v[74:77], v[208:211], v[118:121]
	v_mfma_f32_16x16x32_bf16 v[118:121], v[78:81], v[212:215], v[118:121]
	v_mfma_f32_16x16x32_bf16 v[138:141], v[82:85], v[86:89], v[138:141]
	v_mfma_f32_16x16x32_bf16 v[138:141], v[146:149], v[182:185], v[138:141]
	v_mfma_f32_16x16x32_bf16 v[130:133], v[82:85], v[192:195], v[130:133]
	v_mfma_f32_16x16x32_bf16 v[130:133], v[146:149], v[196:199], v[130:133]
	v_mfma_f32_16x16x32_bf16 v[122:125], v[82:85], v[200:203], v[122:125]
	v_mfma_f32_16x16x32_bf16 v[122:125], v[146:149], v[204:207], v[122:125]
	v_mfma_f32_16x16x32_bf16 v[114:117], v[82:85], v[208:211], v[114:117]
	v_mfma_f32_16x16x32_bf16 v[114:117], v[146:149], v[212:215], v[114:117]
	s_setprio 0
	s_setprio 1
	v_mfma_f32_16x16x32_bf16 v[62:65], v[150:153], v[86:89], v[62:65]
	v_mfma_f32_16x16x32_bf16 v[62:65], v[154:157], v[182:185], v[62:65]
	v_mfma_f32_16x16x32_bf16 v[54:57], v[150:153], v[192:195], v[54:57]
	v_mfma_f32_16x16x32_bf16 v[54:57], v[154:157], v[196:199], v[54:57]
	v_mfma_f32_16x16x32_bf16 v[46:49], v[150:153], v[200:203], v[46:49]
	v_mfma_f32_16x16x32_bf16 v[46:49], v[154:157], v[204:207], v[46:49]
	v_mfma_f32_16x16x32_bf16 v[38:41], v[150:153], v[208:211], v[38:41]
	v_mfma_f32_16x16x32_bf16 v[38:41], v[154:157], v[212:215], v[38:41]
	v_mfma_f32_16x16x32_bf16 v[58:61], v[158:161], v[86:89], v[58:61]
	v_mfma_f32_16x16x32_bf16 v[58:61], v[178:181], v[182:185], v[58:61]
	v_mfma_f32_16x16x32_bf16 v[50:53], v[158:161], v[192:195], v[50:53]
	v_mfma_f32_16x16x32_bf16 v[50:53], v[178:181], v[196:199], v[50:53]
	v_mfma_f32_16x16x32_bf16 v[42:45], v[158:161], v[200:203], v[42:45]
	v_mfma_f32_16x16x32_bf16 v[42:45], v[178:181], v[204:207], v[42:45]
	v_mfma_f32_16x16x32_bf16 v[34:37], v[158:161], v[208:211], v[34:37]
	v_mfma_f32_16x16x32_bf16 v[34:37], v[178:181], v[212:215], v[34:37]
	s_setprio 0
	s_barrier
	s_add_u32 s0, s8, 0x80
	s_addc_u32 s1, s9, 0
	s_add_i32 s10, s31, s12
	ds_read_b128 v[182:185], v223 offset:49152
	ds_read_b128 v[192:195], v223 offset:50176
	ds_read_b128 v[196:199], v223 offset:51200
	ds_read_b128 v[200:203], v223 offset:52224
	ds_read_b128 v[204:207], v223 offset:53248
	ds_read_b128 v[208:211], v223 offset:54272
	ds_read_b128 v[212:215], v223 offset:55296
	ds_read_b128 v[224:227], v223 offset:56320
	s_mov_b32 m0, s10
	s_nop 0
	global_load_lds_dwordx4 v189, s[0:1]
	s_add_i32 m0, s10, 0x2000
	s_nop 0
	global_load_lds_dwordx4 v219, s[0:1]
	s_add_u32 s0, s8, 0x80080
	s_addc_u32 s1, s9, 0
	s_add_i32 s8, s33, s12
	s_mov_b32 m0, s8
	s_nop 0
	global_load_lds_dwordx4 v189, s[0:1]
	s_add_i32 m0, s8, 0x2000
	s_nop 0
	global_load_lds_dwordx4 v219, s[0:1]
	s_mov_b32 m0, s19
	s_nop 0
	global_load_lds_dwordx4 v1, s[6:7]
	s_mov_b32 m0, s20
	s_nop 0
	global_load_lds_dwordx4 v191, s[6:7]
	s_waitcnt vmcnt(8)
	s_waitcnt lgkmcnt(0)
	s_barrier
	s_setprio 1
	s_waitcnt lgkmcnt(0)
	v_mfma_f32_16x16x32_bf16 v[86:89], v[74:77], v[182:185], v[110:113]
	v_mfma_f32_16x16x32_bf16 v[110:113], v[78:81], v[192:195], v[86:89]
	v_mfma_f32_16x16x32_bf16 v[66:69], v[74:77], v[212:215], v[66:69]
	v_mfma_f32_16x16x32_bf16 v[86:89], v[82:85], v[182:185], v[106:109]
	v_mfma_f32_16x16x32_bf16 v[106:109], v[146:149], v[192:195], v[86:89]
	v_mfma_f32_16x16x32_bf16 v[86:89], v[74:77], v[196:199], v[102:105]
	v_mfma_f32_16x16x32_bf16 v[102:105], v[78:81], v[200:203], v[86:89]
	v_mfma_f32_16x16x32_bf16 v[86:89], v[82:85], v[196:199], v[98:101]
	v_mfma_f32_16x16x32_bf16 v[98:101], v[146:149], v[200:203], v[86:89]
	v_mfma_f32_16x16x32_bf16 v[86:89], v[74:77], v[204:207], v[94:97]
	v_mfma_f32_16x16x32_bf16 v[94:97], v[78:81], v[208:211], v[86:89]
	v_mfma_f32_16x16x32_bf16 v[86:89], v[82:85], v[204:207], v[90:93]
	v_mfma_f32_16x16x32_bf16 v[90:93], v[146:149], v[208:211], v[86:89]
	v_mfma_f32_16x16x32_bf16 v[86:89], v[78:81], v[224:227], v[66:69]
	v_mfma_f32_16x16x32_bf16 v[66:69], v[82:85], v[212:215], v[70:73]
	v_mfma_f32_16x16x32_bf16 v[82:85], v[146:149], v[224:227], v[66:69]
	s_setprio 0
	s_setprio 1
	v_mfma_f32_16x16x32_bf16 v[30:33], v[150:153], v[182:185], v[30:33]
	v_mfma_f32_16x16x32_bf16 v[30:33], v[154:157], v[192:195], v[30:33]
	v_mfma_f32_16x16x32_bf16 v[22:25], v[150:153], v[196:199], v[22:25]
	v_mfma_f32_16x16x32_bf16 v[22:25], v[154:157], v[200:203], v[22:25]
	v_mfma_f32_16x16x32_bf16 v[14:17], v[150:153], v[204:207], v[14:17]
	v_mfma_f32_16x16x32_bf16 v[14:17], v[154:157], v[208:211], v[14:17]
	v_mfma_f32_16x16x32_bf16 v[6:9], v[150:153], v[212:215], v[6:9]
	v_mfma_f32_16x16x32_bf16 v[6:9], v[154:157], v[224:227], v[6:9]
	v_mfma_f32_16x16x32_bf16 v[26:29], v[158:161], v[182:185], v[26:29]
	v_mfma_f32_16x16x32_bf16 v[26:29], v[178:181], v[192:195], v[26:29]
	v_mfma_f32_16x16x32_bf16 v[18:21], v[158:161], v[196:199], v[18:21]
	v_mfma_f32_16x16x32_bf16 v[18:21], v[178:181], v[200:203], v[18:21]
	v_mfma_f32_16x16x32_bf16 v[10:13], v[158:161], v[204:207], v[10:13]
	v_mfma_f32_16x16x32_bf16 v[10:13], v[178:181], v[208:211], v[10:13]
	v_mfma_f32_16x16x32_bf16 v[2:5], v[158:161], v[212:215], v[2:5]
	v_mfma_f32_16x16x32_bf16 v[2:5], v[178:181], v[224:227], v[2:5]
	s_setprio 0
	s_barrier
	s_add_i32 s30, s30, 2
	s_add_u32 s28, s28, 0x100
	s_addc_u32 s29, s29, 0
	s_cmp_gt_u32 s30, 29
	s_mov_b64 s[0:1], s[2:3]
	s_cbranch_scc0 .LBB0_232
	s_and_b64 vcc, exec, s[44:45]
	s_cbranch_vccz .LBB0_235
	s_barrier

; #define PG8_STAGE(bufoff, gbase, voff) do { const char* gb_ = (const char*)(gbase); asm volatile("" : "+s"(gb_)); _Pragma("unroll") for (int _i = 0; _i < 2; ++_i) { unsigned vo_ = (voff)[_i]; asm volatile("" : "+v"(vo_));        \
;         __builtin_amdgcn_global_load_lds((const unsigned*)(gb_ + vo_), (PG8_LAS unsigned*)(lds + (bufoff) + ldsw + _i * 8192), 16, 0, 0); } } while (0)
; #define PG8_LDA(dst, b, h) do { _Pragma("unroll") for (int m = 0; m < 4; ++m) _Pragma("unroll") for (int k = 0; k < 2; ++k) dst[m][k] = *(const PG8_LAS bf16x8*)(lds + PG8_SA(b, h) + aoff + m * 2048 + k * 1024); } while (0)
; #define PG8_LDB(dst, b, h) do { _Pragma("unroll") for (int n = 0; n < 2; ++n) _Pragma("unroll") for (int k = 0; k < 2; ++k) dst[n][k] = *(const PG8_LAS bf16x8*)(lds + PG8_SB(b, h) + boff + n * 2048 + k * 1024); } while (0)
; #define PG8_MMA(ai, bj, At, Bt) do { __builtin_amdgcn_s_setprio(1); _Pragma("unroll") for (int m = 0; m < 4; ++m) _Pragma("unroll") for (int n = 0; n < 2; ++n) _Pragma("unroll") for (int k = 0; k < 2; ++k) \
;         acc[ai][bj][m][n] = __builtin_amdgcn_mfma_f32_16x16x32_bf16(Bt[n][k], At[m][k], acc[ai][bj][m][n], 0, 0, 0); __builtin_amdgcn_s_setprio(0); } while (0)
; #define PG8_WAIT_V(n) asm volatile("s_waitcnt vmcnt(" #n ")" ::: "memory")
; template <class Epi, class Sched, bool ALIGN_EPI = false, bool SP2 = false>
; __device__ __forceinline__ void gemm_phase(PG8_LAS unsigned char* lds, const Gemm g, const Sched& S, const Epi& E) {
;     ...
;             const bool last = (t == nt - 2);
;             const char* a1 = cA + (size_t)(t + 1) * kstep;
;             const char* a2 = last ? nA : cA + (size_t)(t + 2) * kstep; const char* b2 = last ? nB : cB + (size_t)(t + 2) * kstep;
;             const char* a3 = a2 + kstep; const char* b3 = b2 + kstep;
;             if (last && has_next) S.a_ready(nxt);
;             if constexpr (SP2) {
;             PG8_LDB(B0, 0, 0); PG8_LDB(B1, 0, 1); PG8_SCHED; PG8_LDA(At, 0, 0); PG8_STAGE(PG8_SA(1, 1), a1 + hstep, voffA);
;             PG8_WAIT_V(8); PG8_WAIT_L(0); PG8_BAR; PG8_MMA(0, 0, At, B0); PG8_MMA(0, 1, At, B1); PG8_BAR; PG8_SCHED;
;             PG8_LDA(At, 0, 1); PG8_STAGE(PG8_SB(0, 0), b2, voffB); PG8_STAGE(PG8_SB(0, 1), b2 + hstep, voffB); PG8_STAGE(PG8_SA(0, 0), a2, voffA);
;             PG8_WAIT_V(8); PG8_WAIT_L(0); PG8_BAR; PG8_MMA(1, 0, At, B0); PG8_MMA(1, 1, At, B1); PG8_BAR; PG8_SCHED;
.LBB0_555:
	s_add_u32 s6, s4, 0x100
	s_addc_u32 s7, s5, 0
	s_cmp_eq_u32 s51, 28
	s_cselect_b32 s12, s35, s6
	s_cselect_b32 s13, s34, s7
	s_cselect_b32 s10, s39, s40
	s_cselect_b32 s11, s38, s49
	s_add_u32 s8, s12, 0x80
	s_addc_u32 s9, s13, 0
	s_add_i32 s56, 0, 0x10000
	s_add_i32 s57, 0, 0x14000
	ds_read_b128 v[26:29], v244
	ds_read_b128 v[30:33], v244 offset:1024
	ds_read_b128 v[98:101], v244 offset:2048
	ds_read_b128 v[102:105], v244 offset:3072
	ds_read_b128 v[146:149], v244 offset:16384
	ds_read_b128 v[150:153], v244 offset:17408
	ds_read_b128 v[154:157], v244 offset:18432
	ds_read_b128 v[158:161], v244 offset:19456
	s_add_u32 s4, s4, 0x80080
	s_addc_u32 s5, s5, 0
	ds_read_b128 v[178:181], v210
	ds_read_b128 v[182:185], v210 offset:1024
	ds_read_b128 v[186:189], v210 offset:2048
	ds_read_b128 v[190:193], v210 offset:3072
	ds_read_b128 v[194:197], v210 offset:4096
	ds_read_b128 v[198:201], v210 offset:5120
	ds_read_b128 v[202:205], v210 offset:6144
	ds_read_b128 v[212:215], v210 offset:7168
	s_add_i32 m0, s18, 0xc000
	s_nop 0
	global_load_lds_dwordx4 v1, s[4:5]
	s_add_i32 m0, s18, 0xe000
	s_nop 0
	global_load_lds_dwordx4 v164, s[4:5]
	s_waitcnt vmcnt(8)
	s_waitcnt lgkmcnt(0)
	s_barrier
	s_setprio 1
	s_waitcnt lgkmcnt(0)
	v_mfma_f32_16x16x32_bf16 v[142:145], v[26:29], v[178:181], v[142:145]
	v_mfma_f32_16x16x32_bf16 v[142:145], v[30:33], v[182:185], v[142:145]
	v_mfma_f32_16x16x32_bf16 v[134:137], v[26:29], v[186:189], v[134:137]
	v_mfma_f32_16x16x32_bf16 v[134:137], v[30:33], v[190:193], v[134:137]
	v_mfma_f32_16x16x32_bf16 v[126:129], v[26:29], v[194:197], v[126:129]
	v_mfma_f32_16x16x32_bf16 v[126:129], v[30:33], v[198:201], v[126:129]
	v_mfma_f32_16x16x32_bf16 v[118:121], v[26:29], v[202:205], v[118:121]
	v_mfma_f32_16x16x32_bf16 v[118:121], v[30:33], v[212:215], v[118:121]
	v_mfma_f32_16x16x32_bf16 v[138:141], v[98:101], v[178:181], v[138:141]
	v_mfma_f32_16x16x32_bf16 v[138:141], v[102:105], v[182:185], v[138:141]
	v_mfma_f32_16x16x32_bf16 v[130:133], v[98:101], v[186:189], v[130:133]
	v_mfma_f32_16x16x32_bf16 v[130:133], v[102:105], v[190:193], v[130:133]
	v_mfma_f32_16x16x32_bf16 v[122:125], v[98:101], v[194:197], v[122:125]
	v_mfma_f32_16x16x32_bf16 v[122:125], v[102:105], v[198:201], v[122:125]
	v_mfma_f32_16x16x32_bf16 v[114:117], v[98:101], v[202:205], v[114:117]
	v_mfma_f32_16x16x32_bf16 v[114:117], v[102:105], v[212:215], v[114:117]
	s_setprio 0
	s_setprio 1
	v_mfma_f32_16x16x32_bf16 v[70:73], v[146:149], v[178:181], v[70:73]
	v_mfma_f32_16x16x32_bf16 v[70:73], v[150:153], v[182:185], v[70:73]
	v_mfma_f32_16x16x32_bf16 v[62:65], v[146:149], v[186:189], v[62:65]
	v_mfma_f32_16x16x32_bf16 v[62:65], v[150:153], v[190:193], v[62:65]
	v_mfma_f32_16x16x32_bf16 v[54:57], v[146:149], v[194:197], v[54:57]
	v_mfma_f32_16x16x32_bf16 v[54:57], v[150:153], v[198:201], v[54:57]
	v_mfma_f32_16x16x32_bf16 v[46:49], v[146:149], v[202:205], v[46:49]
	v_mfma_f32_16x16x32_bf16 v[46:49], v[150:153], v[212:215], v[46:49]
	v_mfma_f32_16x16x32_bf16 v[66:69], v[154:157], v[178:181], v[66:69]
	v_mfma_f32_16x16x32_bf16 v[66:69], v[158:161], v[182:185], v[66:69]
	v_mfma_f32_16x16x32_bf16 v[58:61], v[154:157], v[186:189], v[58:61]
	v_mfma_f32_16x16x32_bf16 v[58:61], v[158:161], v[190:193], v[58:61]
	v_mfma_f32_16x16x32_bf16 v[50:53], v[154:157], v[194:197], v[50:53]
	v_mfma_f32_16x16x32_bf16 v[50:53], v[158:161], v[198:201], v[50:53]
	v_mfma_f32_16x16x32_bf16 v[42:45], v[154:157], v[202:205], v[42:45]
	v_mfma_f32_16x16x32_bf16 v[42:45], v[158:161], v[212:215], v[42:45]
	s_setprio 0
	s_barrier
	s_mov_b64 s[4:5], s[10:11]
	s_add_i32 s56, s56, s17
	ds_read_b128 v[178:181], v210 offset:16384
	ds_read_b128 v[182:185], v210 offset:17408
	ds_read_b128 v[186:189], v210 offset:18432
	ds_read_b128 v[190:193], v210 offset:19456
	ds_read_b128 v[194:197], v210 offset:20480
	ds_read_b128 v[198:201], v210 offset:21504
	ds_read_b128 v[202:205], v210 offset:22528
	ds_read_b128 v[212:215], v210 offset:23552
	s_mov_b32 m0, s56
	s_nop 0
	global_load_lds_dwordx4 v162, s[4:5]
	s_add_i32 m0, s56, 0x2000
	s_nop 0
	global_load_lds_dwordx4 v206, s[4:5]
	s_add_u32 s4, s10, 0x80000
	s_addc_u32 s5, s11, 0
	s_add_i32 s56, s57, s17
	s_mov_b32 m0, s56
	s_nop 0
	global_load_lds_dwordx4 v162, s[4:5]
	s_add_i32 m0, s56, 0x2000
	s_nop 0
	global_load_lds_dwordx4 v206, s[4:5]
	s_mov_b64 s[4:5], s[12:13]
	s_mov_b32 m0, s18
	s_nop 0
	global_load_lds_dwordx4 v1, s[4:5]
	s_mov_b32 m0, s19
	s_nop 0
	global_load_lds_dwordx4 v164, s[4:5]
	s_waitcnt vmcnt(8)
	s_waitcnt lgkmcnt(0)
	s_barrier
; #define PG8_STAGE(bufoff, gbase, voff) do { const char* gb_ = (const char*)(gbase); asm volatile("" : "+s"(gb_)); _Pragma("unroll") for (int _i = 0; _i < 2; ++_i) { unsigned vo_ = (voff)[_i]; asm volatile("" : "+v"(vo_));        \
;         __builtin_amdgcn_global_load_lds((const unsigned*)(gb_ + vo_), (PG8_LAS unsigned*)(lds + (bufoff) + ldsw + _i * 8192), 16, 0, 0); } } while (0)
; #define PG8_LDA(dst, b, h) do { _Pragma("unroll") for (int m = 0; m < 4; ++m) _Pragma("unroll") for (int k = 0; k < 2; ++k) dst[m][k] = *(const PG8_LAS bf16x8*)(lds + PG8_SA(b, h) + aoff + m * 2048 + k * 1024); } while (0)
; #define PG8_LDB(dst, b, h) do { _Pragma("unroll") for (int n = 0; n < 2; ++n) _Pragma("unroll") for (int k = 0; k < 2; ++k) dst[n][k] = *(const PG8_LAS bf16x8*)(lds + PG8_SB(b, h) + boff + n * 2048 + k * 1024); } while (0)
; #define PG8_MMA(ai, bj, At, Bt) do { __builtin_amdgcn_s_setprio(1); _Pragma("unroll") for (int m = 0; m < 4; ++m) _Pragma("unroll") for (int n = 0; n < 2; ++n) _Pragma("unroll") for (int k = 0; k < 2; ++k) \
;         acc[ai][bj][m][n] = __builtin_amdgcn_mfma_f32_16x16x32_bf16(Bt[n][k], At[m][k], acc[ai][bj][m][n], 0, 0, 0); __builtin_amdgcn_s_setprio(0); } while (0)
; #define PG8_WAIT_V(n) asm volatile("s_waitcnt vmcnt(" #n ")" ::: "memory")
; #define PG8_WAIT_L(n) asm volatile("s_waitcnt lgkmcnt(" #n ")" ::: "memory")
; #define PG8_BAR __builtin_amdgcn_s_barrier()
; #define PG8_SCHED __builtin_amdgcn_sched_barrier(0)
; template <class Epi, class Sched, bool ALIGN_EPI = false, bool SP2 = false>
; __device__ __forceinline__ void gemm_phase(PG8_LAS unsigned char* lds, const Gemm g, const Sched& S, const Epi& E) {
;     ...
;             PG8_WAIT_V(8); PG8_WAIT_L(0); PG8_BAR; PG8_MMA(0, 0, At, B0); PG8_MMA(0, 1, At, B1); PG8_BAR; PG8_SCHED;
;             PG8_LDA(At, 0, 1); PG8_STAGE(PG8_SB(0, 0), b2, voffB); PG8_STAGE(PG8_SB(0, 1), b2 + hstep, voffB); PG8_STAGE(PG8_SA(0, 0), a2, voffA);
;             PG8_WAIT_V(8); PG8_WAIT_L(0); PG8_BAR; PG8_MMA(1, 0, At, B0); PG8_MMA(1, 1, At, B1); PG8_BAR; PG8_SCHED;
;             PG8_LDB(B0, 1, 0); PG8_LDB(B1, 1, 1); PG8_SCHED; PG8_LDA(At, 1, 0); PG8_STAGE(PG8_SA(0, 1), a2 + hstep, voffA);
;             PG8_WAIT_V(8); PG8_WAIT_L(0); PG8_BAR; PG8_MMA(0, 0, At, B0); PG8_MMA(0, 1, At, B1); PG8_BAR; PG8_SCHED;
	s_setprio 1
	s_waitcnt lgkmcnt(0)
	v_mfma_f32_16x16x32_bf16 v[110:113], v[26:29], v[178:181], v[110:113]
	v_mfma_f32_16x16x32_bf16 v[110:113], v[30:33], v[182:185], v[110:113]
	v_mfma_f32_16x16x32_bf16 v[94:97], v[26:29], v[186:189], v[94:97]
	v_mfma_f32_16x16x32_bf16 v[94:97], v[30:33], v[190:193], v[94:97]
	v_mfma_f32_16x16x32_bf16 v[86:89], v[26:29], v[194:197], v[86:89]
	v_mfma_f32_16x16x32_bf16 v[86:89], v[30:33], v[198:201], v[86:89]
	v_mfma_f32_16x16x32_bf16 v[26:29], v[26:29], v[202:205], v[78:81]
	v_mfma_f32_16x16x32_bf16 v[26:29], v[30:33], v[212:215], v[26:29]
	v_mfma_f32_16x16x32_bf16 v[106:109], v[98:101], v[178:181], v[106:109]
	v_mfma_f32_16x16x32_bf16 v[106:109], v[102:105], v[182:185], v[106:109]
	v_mfma_f32_16x16x32_bf16 v[90:93], v[98:101], v[186:189], v[90:93]
	v_mfma_f32_16x16x32_bf16 v[90:93], v[102:105], v[190:193], v[90:93]
	v_mfma_f32_16x16x32_bf16 v[82:85], v[98:101], v[194:197], v[82:85]
	v_mfma_f32_16x16x32_bf16 v[82:85], v[102:105], v[198:201], v[82:85]
	v_mfma_f32_16x16x32_bf16 v[30:33], v[98:101], v[202:205], v[74:77]
	v_mfma_f32_16x16x32_bf16 v[30:33], v[102:105], v[212:215], v[30:33]
	s_setprio 0
	s_setprio 1
	v_mfma_f32_16x16x32_bf16 v[38:41], v[146:149], v[178:181], v[38:41]
	v_mfma_f32_16x16x32_bf16 v[38:41], v[150:153], v[182:185], v[38:41]
	v_mfma_f32_16x16x32_bf16 v[22:25], v[146:149], v[186:189], v[22:25]
	v_mfma_f32_16x16x32_bf16 v[22:25], v[150:153], v[190:193], v[22:25]
	v_mfma_f32_16x16x32_bf16 v[14:17], v[146:149], v[194:197], v[14:17]
	v_mfma_f32_16x16x32_bf16 v[14:17], v[150:153], v[198:201], v[14:17]
	v_mfma_f32_16x16x32_bf16 v[6:9], v[146:149], v[202:205], v[6:9]
	v_mfma_f32_16x16x32_bf16 v[6:9], v[150:153], v[212:215], v[6:9]
	v_mfma_f32_16x16x32_bf16 v[34:37], v[154:157], v[178:181], v[34:37]
	v_mfma_f32_16x16x32_bf16 v[34:37], v[158:161], v[182:185], v[34:37]
	v_mfma_f32_16x16x32_bf16 v[18:21], v[154:157], v[186:189], v[18:21]
	v_mfma_f32_16x16x32_bf16 v[18:21], v[158:161], v[190:193], v[18:21]
	v_mfma_f32_16x16x32_bf16 v[10:13], v[154:157], v[194:197], v[10:13]
	v_mfma_f32_16x16x32_bf16 v[10:13], v[158:161], v[198:201], v[10:13]
	v_mfma_f32_16x16x32_bf16 v[2:5], v[154:157], v[202:205], v[2:5]
	v_mfma_f32_16x16x32_bf16 v[2:5], v[158:161], v[212:215], v[2:5]
	s_setprio 0
	s_barrier
	s_add_i32 s56, 0, 0x18000
	s_add_i32 s57, 0, 0x1c000
	ds_read_b128 v[74:77], v244 offset:32768
	ds_read_b128 v[78:81], v244 offset:33792
	ds_read_b128 v[98:101], v244 offset:34816
	ds_read_b128 v[102:105], v244 offset:35840
	ds_read_b128 v[146:149], v244 offset:49152
	ds_read_b128 v[150:153], v244 offset:50176
	ds_read_b128 v[154:157], v244 offset:51200
	ds_read_b128 v[158:161], v244 offset:52224
	s_add_u32 s4, s12, 0x80000
	s_addc_u32 s5, s13, 0
	s_mov_b32 m0, s20
	ds_read_b128 v[178:181], v210 offset:32768
	ds_read_b128 v[182:185], v210 offset:33792
	ds_read_b128 v[186:189], v210 offset:34816
	ds_read_b128 v[190:193], v210 offset:35840
	ds_read_b128 v[194:197], v210 offset:36864
	ds_read_b128 v[198:201], v210 offset:37888
	ds_read_b128 v[202:205], v210 offset:38912
	ds_read_b128 v[212:215], v210 offset:39936
	s_nop 0
	global_load_lds_dwordx4 v1, s[4:5]
	s_mov_b32 m0, s21
	s_nop 0
	global_load_lds_dwordx4 v164, s[4:5]
	s_waitcnt vmcnt(8)
	s_waitcnt lgkmcnt(0)
	s_barrier
	s_setprio 1
	s_waitcnt lgkmcnt(0)
	v_mfma_f32_16x16x32_bf16 v[142:145], v[74:77], v[178:181], v[142:145]
	v_mfma_f32_16x16x32_bf16 v[142:145], v[78:81], v[182:185], v[142:145]
	v_mfma_f32_16x16x32_bf16 v[134:137], v[74:77], v[186:189], v[134:137]
	v_mfma_f32_16x16x32_bf16 v[134:137], v[78:81], v[190:193], v[134:137]
	v_mfma_f32_16x16x32_bf16 v[126:129], v[74:77], v[194:197], v[126:129]
	v_mfma_f32_16x16x32_bf16 v[126:129], v[78:81], v[198:201], v[126:129]
	v_mfma_f32_16x16x32_bf16 v[118:121], v[74:77], v[202:205], v[118:121]
	v_mfma_f32_16x16x32_bf16 v[118:121], v[78:81], v[212:215], v[118:121]
	v_mfma_f32_16x16x32_bf16 v[138:141], v[98:101], v[178:181], v[138:141]
	v_mfma_f32_16x16x32_bf16 v[138:141], v[102:105], v[182:185], v[138:141]
	v_mfma_f32_16x16x32_bf16 v[130:133], v[98:101], v[186:189], v[130:133]
	v_mfma_f32_16x16x32_bf16 v[130:133], v[102:105], v[190:193], v[130:133]
	v_mfma_f32_16x16x32_bf16 v[122:125], v[98:101], v[194:197], v[122:125]
	v_mfma_f32_16x16x32_bf16 v[122:125], v[102:105], v[198:201], v[122:125]
	v_mfma_f32_16x16x32_bf16 v[114:117], v[98:101], v[202:205], v[114:117]
	v_mfma_f32_16x16x32_bf16 v[114:117], v[102:105], v[212:215], v[114:117]
	s_setprio 0
	s_setprio 1
	v_mfma_f32_16x16x32_bf16 v[70:73], v[146:149], v[178:181], v[70:73]
	v_mfma_f32_16x16x32_bf16 v[70:73], v[150:153], v[182:185], v[70:73]
	v_mfma_f32_16x16x32_bf16 v[62:65], v[146:149], v[186:189], v[62:65]
	v_mfma_f32_16x16x32_bf16 v[62:65], v[150:153], v[190:193], v[62:65]
	v_mfma_f32_16x16x32_bf16 v[54:57], v[146:149], v[194:197], v[54:57]
	v_mfma_f32_16x16x32_bf16 v[54:57], v[150:153], v[198:201], v[54:57]
	v_mfma_f32_16x16x32_bf16 v[46:49], v[146:149], v[202:205], v[46:49]
	v_mfma_f32_16x16x32_bf16 v[46:49], v[150:153], v[212:215], v[46:49]
	v_mfma_f32_16x16x32_bf16 v[66:69], v[154:157], v[178:181], v[66:69]
	v_mfma_f32_16x16x32_bf16 v[66:69], v[158:161], v[182:185], v[66:69]
	v_mfma_f32_16x16x32_bf16 v[58:61], v[154:157], v[186:189], v[58:61]
	v_mfma_f32_16x16x32_bf16 v[58:61], v[158:161], v[190:193], v[58:61]
	v_mfma_f32_16x16x32_bf16 v[50:53], v[154:157], v[194:197], v[50:53]
	v_mfma_f32_16x16x32_bf16 v[50:53], v[158:161], v[198:201], v[50:53]
	v_mfma_f32_16x16x32_bf16 v[42:45], v[154:157], v[202:205], v[42:45]
	v_mfma_f32_16x16x32_bf16 v[42:45], v[158:161], v[212:215], v[42:45]
	s_setprio 0
	s_barrier
;     __device__ __forceinline__ void operator()(const f32x4 (&acc)[2][2][4][2], const Unit& u, int wr, int wc, int fr, int fq) const {
;         const int row0 = u.pm * BM + wr * 64 + fr, col0 = u.pn * BM + wc * 32 + 8 * fq, b = (u.pm * BM) / rows_per_batch;
;         const float* g = gate + (size_t)b * gate_bstride + col0;
;         float ssq[2][4];
; #pragma unroll
;         for (int ai = 0; ai < 2; ++ai)
; #pragma unroll
;             for (int m = 0; m < 4; ++m) ssq[ai][m] = 0.f;
;         f32x4 gv[2][2], Gv[2][2];
; #pragma unroll
;         for (int bj = 0; bj < 2; ++bj) { gv[bj][0] = *(const f32x4*)(g + bj * HALF); gv[bj][1] = *(const f32x4*)(g + bj * HALF + 4); Gv[bj][0] = (f32x4){0.f, 0.f, 0.f, 0.f}; Gv[bj][1] = (f32x4){0.f, 0.f, 0.f, 0.f};
;             if (Hn) { const float* sc = scnext + (size_t)b * gate_bstride + col0 + bj * HALF;
;                 Gv[bj][0] = *(const f32x4*)(gnext + col0 + bj * HALF) * (1.0f + *(const f32x4*)(sc)); Gv[bj][1] = *(const f32x4*)(gnext + col0 + bj * HALF + 4) * (1.0f + *(const f32x4*)(sc + 4)); } }
; #pragma unroll
;         for (int bj = 0; bj < 2; ++bj) {
;             const f32x4 g0 = gv[bj][0], g1 = gv[bj][1], G0 = Gv[bj][0], G1 = Gv[bj][1];
; #pragma unroll
;             for (int ai = 0; ai < 2; ++ai)
; #pragma unroll
;                 for (int m = 0; m < 4; ++m) { const size_t off = (size_t)(row0 + ai * HALF + m * 16) * 2048 + col0 + bj * HALF;
;                     f32x4 x0 = __builtin_nontemporal_load((const f32x4*)(base + off)), x1 = __builtin_nontemporal_load((const f32x4*)(base + off + 4));
;                     if constexpr (HAS_DIN) { const u32x4 dw = __builtin_nontemporal_load((const u32x4*)(dbuf + off));
; template <class Epi, class Sched, bool ALIGN_EPI = false, bool SP2 = false>
; __device__ __forceinline__ void gemm_phase(PG8_LAS unsigned char* lds, const Gemm g, const Sched& S, const Epi& E) {
;     ...
;             PG8_LDB(B0, 1, 0); PG8_LDB(B1, 1, 1); PG8_SCHED; PG8_LDA(At, 1, 0); PG8_STAGE(PG8_SA(0, 1), a2 + hstep, voffA);
;             PG8_WAIT_V(8); PG8_WAIT_L(0); PG8_BAR; PG8_MMA(0, 0, At, B0); PG8_MMA(0, 1, At, B1); PG8_BAR; PG8_SCHED;
;             PG8_LDA(At, 1, 1); PG8_STAGE(PG8_SB(1, 0), b3, voffB); PG8_STAGE(PG8_SB(1, 1), b3 + hstep, voffB); PG8_STAGE(PG8_SA(1, 0), a3, voffA);
;             PG8_WAIT_V(8); PG8_WAIT_L(0); PG8_BAR; PG8_MMA(1, 0, At, B0); PG8_MMA(1, 1, At, B1); PG8_BAR; PG8_SCHED;
	s_add_u32 s4, s10, 0x80
	s_addc_u32 s5, s11, 0
	s_add_i32 s12, s56, s17
	ds_read_b128 v[178:181], v210 offset:49152
	ds_read_b128 v[182:185], v210 offset:50176
	ds_read_b128 v[186:189], v210 offset:51200
	ds_read_b128 v[190:193], v210 offset:52224
	ds_read_b128 v[194:197], v210 offset:53248
	ds_read_b128 v[198:201], v210 offset:54272
	ds_read_b128 v[202:205], v210 offset:55296
	ds_read_b128 v[212:215], v210 offset:56320
	s_mov_b32 m0, s12
	s_nop 0
	global_load_lds_dwordx4 v162, s[4:5]
	s_add_i32 m0, s12, 0x2000
	s_nop 0
	global_load_lds_dwordx4 v206, s[4:5]
	s_add_u32 s4, s10, 0x80080
	s_addc_u32 s5, s11, 0
	s_add_i32 s10, s57, s17
	s_mov_b32 m0, s10
	s_nop 0
	global_load_lds_dwordx4 v162, s[4:5]
	s_add_i32 m0, s10, 0x2000
	s_nop 0
	global_load_lds_dwordx4 v206, s[4:5]
	s_mov_b32 m0, s26
	s_nop 0
	global_load_lds_dwordx4 v1, s[8:9]
	s_mov_b32 m0, s27
	s_nop 0
	global_load_lds_dwordx4 v164, s[8:9]
	s_waitcnt vmcnt(8)
	s_waitcnt lgkmcnt(0)
	s_barrier
	s_setprio 1
	s_waitcnt lgkmcnt(0)
	v_mfma_f32_16x16x32_bf16 v[110:113], v[74:77], v[178:181], v[110:113]
	v_mfma_f32_16x16x32_bf16 v[110:113], v[78:81], v[182:185], v[110:113]
	v_mfma_f32_16x16x32_bf16 v[94:97], v[74:77], v[186:189], v[94:97]
	v_mfma_f32_16x16x32_bf16 v[94:97], v[78:81], v[190:193], v[94:97]
	v_mfma_f32_16x16x32_bf16 v[86:89], v[74:77], v[194:197], v[86:89]
	v_mfma_f32_16x16x32_bf16 v[86:89], v[78:81], v[198:201], v[86:89]
	v_mfma_f32_16x16x32_bf16 v[26:29], v[74:77], v[202:205], v[26:29]
	v_mfma_f32_16x16x32_bf16 v[78:81], v[78:81], v[212:215], v[26:29]
	v_mfma_f32_16x16x32_bf16 v[106:109], v[98:101], v[178:181], v[106:109]
	v_mfma_f32_16x16x32_bf16 v[106:109], v[102:105], v[182:185], v[106:109]
	v_mfma_f32_16x16x32_bf16 v[90:93], v[98:101], v[186:189], v[90:93]
	v_mfma_f32_16x16x32_bf16 v[90:93], v[102:105], v[190:193], v[90:93]
	v_mfma_f32_16x16x32_bf16 v[82:85], v[98:101], v[194:197], v[82:85]
	v_mfma_f32_16x16x32_bf16 v[82:85], v[102:105], v[198:201], v[82:85]
	v_mfma_f32_16x16x32_bf16 v[26:29], v[98:101], v[202:205], v[30:33]
	v_mfma_f32_16x16x32_bf16 v[74:77], v[102:105], v[212:215], v[26:29]
	s_setprio 0
	s_setprio 1
	v_mfma_f32_16x16x32_bf16 v[26:29], v[146:149], v[178:181], v[38:41]
	v_mfma_f32_16x16x32_bf16 v[38:41], v[150:153], v[182:185], v[26:29]
	v_mfma_f32_16x16x32_bf16 v[22:25], v[146:149], v[186:189], v[22:25]
	v_mfma_f32_16x16x32_bf16 v[22:25], v[150:153], v[190:193], v[22:25]
	v_mfma_f32_16x16x32_bf16 v[14:17], v[146:149], v[194:197], v[14:17]
	v_mfma_f32_16x16x32_bf16 v[14:17], v[150:153], v[198:201], v[14:17]
	v_mfma_f32_16x16x32_bf16 v[6:9], v[146:149], v[202:205], v[6:9]
	v_mfma_f32_16x16x32_bf16 v[6:9], v[150:153], v[212:215], v[6:9]
	v_mfma_f32_16x16x32_bf16 v[26:29], v[154:157], v[178:181], v[34:37]
	v_mfma_f32_16x16x32_bf16 v[34:37], v[158:161], v[182:185], v[26:29]
	v_mfma_f32_16x16x32_bf16 v[18:21], v[154:157], v[186:189], v[18:21]
	v_mfma_f32_16x16x32_bf16 v[18:21], v[158:161], v[190:193], v[18:21]
	v_mfma_f32_16x16x32_bf16 v[10:13], v[154:157], v[194:197], v[10:13]
	v_mfma_f32_16x16x32_bf16 v[10:13], v[158:161], v[198:201], v[10:13]
	v_mfma_f32_16x16x32_bf16 v[2:5], v[154:157], v[202:205], v[2:5]
	v_mfma_f32_16x16x32_bf16 v[2:5], v[158:161], v[212:215], v[2:5]
	s_setprio 0
	s_barrier
	s_add_i32 s51, s51, 2
	s_add_u32 s40, s40, 0x100
	s_addc_u32 s49, s49, 0
	s_cmp_gt_u32 s51, 29
	s_mov_b64 s[4:5], s[6:7]
	s_cbranch_scc0 .LBB0_555
	s_ashr_i32 s4, s29, 31
	s_lshr_b32 s4, s4, 27
	s_add_i32 s4, s29, s4
	s_ashr_i32 s4, s4, 5
	v_lshl_or_b32 v148, s33, 8, v209
	s_mul_i32 s7, s4, 0xc000
	v_ashrrev_i32_e32 v149, 31, v148
	s_mul_hi_i32 s6, s4, 0xc000
	s_add_u32 s4, s22, s7
	s_addc_u32 s5, s23, s6
	v_lshlrev_b64 v[26:27], 2, v[148:149]
	v_lshl_add_u64 v[146:147], s[4:5], 0, v[26:27]
	s_add_u32 s4, s24, s7
	s_addc_u32 s5, s25, s6
	v_lshl_add_u64 v[160:161], s[4:5], 0, v[26:27]
	v_lshl_add_u64 v[178:179], s[46:47], 0, v[26:27]
	global_load_dwordx4 v[98:101], v[146:147], off offset:16
	global_load_dwordx4 v[102:105], v[146:147], off
	global_load_dwordx4 v[26:29], v[178:179], off offset:16
	global_load_dwordx4 v[30:33], v[178:179], off
	global_load_dwordx4 v[150:153], v[160:161], off offset:16
	global_load_dwordx4 v[154:157], v[160:161], off
	s_mov_b64 s[4:5], 0x40000
	s_waitcnt vmcnt(0)
	v_pk_mul_f32 v[188:189], v[140:141], v[100:101]
	v_pk_mul_f32 v[142:143], v[142:143], v[102:103]
	v_pk_mul_f32 v[144:145], v[144:145], v[104:105]
	v_pk_mul_f32 v[140:141], v[138:139], v[98:99]
	v_pk_mul_f32 v[136:137], v[136:137], v[104:105]
	v_pk_add_f32 v[156:157], v[156:157], 1.0 op_sel_hi:[1,0]
	v_pk_add_f32 v[154:155], v[154:155], 1.0 op_sel_hi:[1,0]
	v_pk_mul_f32 v[198:199], v[32:33], v[156:157]
	v_pk_mul_f32 v[200:201], v[30:31], v[154:155]
	v_pk_add_f32 v[30:31], v[152:153], 1.0 op_sel_hi:[1,0]
	v_pk_add_f32 v[32:33], v[150:151], 1.0 op_sel_hi:[1,0]
	v_pk_mul_f32 v[202:203], v[28:29], v[30:31]
	v_pk_mul_f32 v[204:205], v[26:27], v[32:33]
	global_load_dwordx4 v[26:29], v[146:147], off offset:528
	global_load_dwordx4 v[30:33], v[146:147], off offset:512
	global_load_dwordx4 v[156:159], v[178:179], off offset:528
	global_load_dwordx4 v[152:155], v[178:179], off offset:512
	s_nop 0
	global_load_dwordx4 v[178:181], v[160:161], off offset:528
	global_load_dwordx4 v[182:185], v[160:161], off offset:512
	v_pk_mul_f32 v[134:135], v[134:135], v[102:103]
	v_pk_mul_f32 v[130:131], v[130:131], v[98:99]
	v_pk_mul_f32 v[132:133], v[132:133], v[100:101]
	v_pk_mul_f32 v[128:129], v[128:129], v[104:105]
	v_pk_mul_f32 v[126:127], v[126:127], v[102:103]
	v_pk_mul_f32 v[122:123], v[122:123], v[98:99]
	v_pk_mul_f32 v[124:125], v[124:125], v[100:101]
	v_pk_mul_f32 v[120:121], v[120:121], v[104:105]
	v_pk_mul_f32 v[118:119], v[118:119], v[102:103]
	v_pk_mul_f32 v[114:115], v[114:115], v[98:99]
	v_pk_mul_f32 v[116:117], v[116:117], v[100:101]
	v_pk_mul_f32 v[112:113], v[112:113], v[104:105]
	v_pk_mul_f32 v[110:111], v[110:111], v[102:103]
	v_pk_mul_f32 v[106:107], v[106:107], v[98:99]
	v_pk_mul_f32 v[108:109], v[108:109], v[100:101]
	v_pk_mul_f32 v[96:97], v[96:97], v[104:105]
	v_pk_mul_f32 v[94:95], v[94:95], v[102:103]
	v_pk_mul_f32 v[90:91], v[90:91], v[98:99]
	v_pk_mul_f32 v[92:93], v[92:93], v[100:101]
	v_pk_mul_f32 v[88:89], v[88:89], v[104:105]
	v_pk_mul_f32 v[86:87], v[86:87], v[102:103]
	v_pk_mul_f32 v[82:83], v[82:83], v[98:99]
	v_pk_mul_f32 v[84:85], v[84:85], v[100:101]
	v_pk_mul_f32 v[80:81], v[80:81], v[104:105]
	v_pk_mul_f32 v[78:79], v[78:79], v[102:103]
	v_pk_mul_f32 v[74:75], v[74:75], v[98:99]
	v_pk_mul_f32 v[76:77], v[76:77], v[100:101]
	s_waitcnt vmcnt(5)
;     __device__ __forceinline__ void operator()(const f32x4 (&acc)[2][2][4][2], const Unit& u, int wr, int wc, int fr, int fq) const {
;     ...
;         for (int bj = 0; bj < 2; ++bj) {
;             const f32x4 g0 = gv[bj][0], g1 = gv[bj][1], G0 = Gv[bj][0], G1 = Gv[bj][1];
; #pragma unroll
;             for (int ai = 0; ai < 2; ++ai)
; #pragma unroll
;                 for (int m = 0; m < 4; ++m) { const size_t off = (size_t)(row0 + ai * HALF + m * 16) * 2048 + col0 + bj * HALF;
;                     f32x4 x0 = __builtin_nontemporal_load((const f32x4*)(base + off)), x1 = __builtin_nontemporal_load((const f32x4*)(base + off + 4));
;                     if constexpr (HAS_DIN) { const u32x4 dw = __builtin_nontemporal_load((const u32x4*)(dbuf + off));
;                         x0 += (f32x4){__builtin_bit_cast(float, dw.x << 16), __builtin_bit_cast(float, dw.x & 0xffff0000u), __builtin_bit_cast(float, dw.y << 16), __builtin_bit_cast(float, dw.y & 0xffff0000u)};
;                         x1 += (f32x4){__builtin_bit_cast(float, dw.z << 16), __builtin_bit_cast(float, dw.z & 0xffff0000u), __builtin_bit_cast(float, dw.w << 16), __builtin_bit_cast(float, dw.w & 0xffff0000u)}; }
;                     f32x4 o0, o1;
;                     if constexpr (OUT_DELTA) { const f32x4 d0 = g0 * acc[ai][bj][m][0], d1 = g1 * acc[ai][bj][m][1];
;                         u32x4 w; w.x = cvt_pk_bf16(d0[0], d0[1]); w.y = cvt_pk_bf16(d0[2], d0[3]); w.z = cvt_pk_bf16(d1[0], d1[1]); w.w = cvt_pk_bf16(d1[2], d1[3]);
;                         *(u32x4*)(dbuf + off) = w;
;                         o0 = x0 + (f32x4){__builtin_bit_cast(float, w.x << 16), __builtin_bit_cast(float, w.x & 0xffff0000u), __builtin_bit_cast(float, w.y << 16), __builtin_bit_cast(float, w.y & 0xffff0000u)};
;                         o1 = x1 + (f32x4){__builtin_bit_cast(float, w.z << 16), __builtin_bit_cast(float, w.z & 0xffff0000u), __builtin_bit_cast(float, w.w << 16), __builtin_bit_cast(float, w.w & 0xffff0000u)}; }
;                     else { o0 = x0 + g0 * acc[ai][bj][m][0]; o1 = x1 + g1 * acc[ai][bj][m][1]; *(f32x4*)(out + off) = o0; *(f32x4*)(out + off + 4) = o1; }
;                     if (Hn) { const f32x4 h0 = o0 * G0, h1 = o1 * G1;
;                         u32x4 w; w.x = cvt_pk_bf16(h0[0], h0[1]); w.y = cvt_pk_bf16(h0[2], h0[3]); w.z = cvt_pk_bf16(h1[0], h1[1]); w.w = cvt_pk_bf16(h1[2], h1[3]);
	v_pk_mul_f32 v[58:59], v[58:59], v[26:27]
	s_waitcnt vmcnt(4)
	v_pk_mul_f32 v[72:73], v[72:73], v[32:33]
	v_pk_mul_f32 v[70:71], v[70:71], v[30:31]
	v_pk_mul_f32 v[64:65], v[64:65], v[32:33]
	v_pk_mul_f32 v[62:63], v[62:63], v[30:31]
	s_waitcnt vmcnt(0)
	v_pk_add_f32 v[146:147], v[184:185], 1.0 op_sel_hi:[1,0]
	v_pk_add_f32 v[160:161], v[182:183], 1.0 op_sel_hi:[1,0]
	v_pk_mul_f32 v[150:151], v[154:155], v[146:147]
	v_pk_add_f32 v[146:147], v[180:181], 1.0 op_sel_hi:[1,0]
	v_pk_mul_f32 v[152:153], v[152:153], v[160:161]
	v_pk_mul_f32 v[154:155], v[158:159], v[146:147]
	v_lshl_add_u32 v146, s29, 8, v207
	v_ashrrev_i32_e32 v147, 31, v146
	v_lshlrev_b64 v[184:185], 11, v[146:147]
	v_lshl_add_u64 v[186:187], v[184:185], 0, v[148:149]
	v_pk_add_f32 v[160:161], v[178:179], 1.0 op_sel_hi:[1,0]
	v_lshl_add_u64 v[178:179], v[186:187], 2, s[44:45]
	v_pk_mul_f32 v[156:157], v[156:157], v[160:161]
	global_load_dwordx4 v[158:161], v[178:179], off nt
	global_load_dwordx4 v[180:183], v[178:179], off offset:16 nt
	v_cvt_pk_bf16_f32 v138, v142, v143
	v_lshlrev_b64 v[142:143], 1, v[186:187]
	v_cvt_pk_bf16_f32 v139, v144, v145
	v_cvt_pk_bf16_f32 v140, v140, v141
	v_cvt_pk_bf16_f32 v141, v188, v189
	v_lshl_add_u64 v[144:145], s[90:91], 0, v[142:143]
	global_store_dwordx4 v[144:145], v[138:141], off
	v_lshlrev_b32_e32 v144, 16, v140
	v_and_b32_e32 v145, 0xffff0000, v140
	v_lshlrev_b32_e32 v140, 16, v141
	v_and_b32_e32 v141, 0xffff0000, v141
	v_lshl_add_u64 v[142:143], s[96:97], 0, v[142:143]
	v_pk_mul_f32 v[60:61], v[60:61], v[28:29]
	v_pk_mul_f32 v[56:57], v[56:57], v[32:33]
	v_pk_mul_f32 v[54:55], v[54:55], v[30:31]
	v_pk_mul_f32 v[50:51], v[50:51], v[26:27]
	v_pk_mul_f32 v[52:53], v[52:53], v[28:29]
	v_pk_mul_f32 v[48:49], v[48:49], v[32:33]
	v_pk_mul_f32 v[46:47], v[46:47], v[30:31]
	v_pk_mul_f32 v[42:43], v[42:43], v[26:27]
	v_pk_mul_f32 v[44:45], v[44:45], v[28:29]
	v_pk_mul_f32 v[40:41], v[40:41], v[32:33]
	v_pk_mul_f32 v[38:39], v[38:39], v[30:31]
	v_pk_mul_f32 v[34:35], v[34:35], v[26:27]
	v_pk_mul_f32 v[36:37], v[36:37], v[28:29]
	v_pk_mul_f32 v[24:25], v[24:25], v[32:33]
	v_pk_mul_f32 v[22:23], v[22:23], v[30:31]
	v_pk_mul_f32 v[18:19], v[18:19], v[26:27]
	v_pk_mul_f32 v[20:21], v[20:21], v[28:29]
	v_pk_mul_f32 v[16:17], v[16:17], v[32:33]
	v_pk_mul_f32 v[14:15], v[14:15], v[30:31]
	v_pk_mul_f32 v[10:11], v[10:11], v[26:27]
	v_pk_mul_f32 v[12:13], v[12:13], v[28:29]
	v_pk_mul_f32 v[8:9], v[8:9], v[32:33]
	v_pk_mul_f32 v[6:7], v[6:7], v[30:31]
	v_pk_mul_f32 v[2:3], v[2:3], v[26:27]
	v_pk_mul_f32 v[4:5], v[4:5], v[28:29]
	s_waitcnt vmcnt(1)
	v_pk_add_f32 v[182:183], v[182:183], v[140:141]
	v_lshlrev_b32_e32 v140, 16, v138
	v_and_b32_e32 v141, 0xffff0000, v138
	v_lshlrev_b32_e32 v138, 16, v139
	v_and_b32_e32 v139, 0xffff0000, v139
	v_pk_add_f32 v[158:159], v[158:159], v[140:141]
	v_pk_add_f32 v[160:161], v[160:161], v[138:139]
	v_pk_mul_f32 v[138:139], v[200:201], v[158:159]
	v_pk_add_f32 v[144:145], v[180:181], v[144:145]
	v_pk_mul_f32 v[140:141], v[198:199], v[160:161]
	v_cvt_pk_bf16_f32 v138, v138, v139
	v_pk_mul_f32 v[180:181], v[202:203], v[182:183]
	v_cvt_pk_bf16_f32 v139, v140, v141
	v_pk_mul_f32 v[186:187], v[204:205], v[144:145]
	s_nop 0
	v_cvt_pk_bf16_f32 v140, v186, v187
	v_cvt_pk_bf16_f32 v141, v180, v181
	global_store_dwordx4 v[142:143], v[138:141], off
	s_nop 1
	v_mul_f32_e32 v138, v159, v159
	v_mul_f32_e32 v139, v161, v161
	v_fmac_f32_e32 v138, v158, v158
	v_fmac_f32_e32 v139, v160, v160
	v_add_f32_e32 v138, v138, v139
	v_mul_f32_e32 v139, v145, v145
	v_mul_f32_e32 v140, v183, v183
	v_fmac_f32_e32 v139, v144, v144
	v_fmac_f32_e32 v140, v182, v182
	v_add_f32_e32 v139, v139, v140
	v_add_f32_e32 v211, v138, v139
	v_or_b32_e32 v138, 16, v146
	v_ashrrev_i32_e32 v139, 31, v138
	v_lshlrev_b64 v[140:141], 11, v[138:139]
	v_lshl_add_u64 v[180:181], v[140:141], 0, v[148:149]
	v_lshl_add_u64 v[138:139], v[180:181], 2, s[44:45]
	global_load_dwordx4 v[142:145], v[138:139], off nt
	global_load_dwordx4 v[158:161], v[138:139], off offset:16 nt
	v_lshlrev_b64 v[180:181], 1, v[180:181]
	v_cvt_pk_bf16_f32 v134, v134, v135
	v_cvt_pk_bf16_f32 v135, v136, v137
	v_cvt_pk_bf16_f32 v136, v130, v131
	v_cvt_pk_bf16_f32 v137, v132, v133
	v_lshl_add_u64 v[130:131], s[90:91], 0, v[180:181]
	global_store_dwordx4 v[130:131], v[134:137], off
	v_lshlrev_b32_e32 v132, 16, v136
	v_and_b32_e32 v133, 0xffff0000, v136
	v_lshlrev_b32_e32 v130, 16, v137
	v_and_b32_e32 v131, 0xffff0000, v137
	v_lshlrev_b32_e32 v136, 16, v134
	v_and_b32_e32 v137, 0xffff0000, v134
	v_lshlrev_b32_e32 v134, 16, v135
	v_and_b32_e32 v135, 0xffff0000, v135
	s_waitcnt vmcnt(2)
	v_pk_add_f32 v[134:135], v[144:145], v[134:135]
	s_waitcnt vmcnt(1)
	v_pk_add_f32 v[130:131], v[160:161], v[130:131]
	v_pk_add_f32 v[136:137], v[142:143], v[136:137]
	v_pk_add_f32 v[132:133], v[158:159], v[132:133]
	v_pk_mul_f32 v[144:145], v[198:199], v[134:135]
	v_pk_mul_f32 v[142:143], v[200:201], v[136:137]
	v_pk_mul_f32 v[158:159], v[202:203], v[130:131]
	v_pk_mul_f32 v[160:161], v[204:205], v[132:133]
	v_cvt_pk_bf16_f32 v142, v142, v143
	v_cvt_pk_bf16_f32 v143, v144, v145
	s_nop 0
	v_cvt_pk_bf16_f32 v144, v160, v161
	v_cvt_pk_bf16_f32 v145, v158, v159
	v_lshl_add_u64 v[158:159], s[96:97], 0, v[180:181]
	global_store_dwordx4 v[158:159], v[142:145], off
	s_nop 1
	v_or_b32_e32 v142, 32, v146
	v_ashrrev_i32_e32 v143, 31, v142
	v_lshlrev_b64 v[144:145], 11, v[142:143]
	v_lshl_add_u64 v[186:187], v[144:145], 0, v[148:149]
	v_lshl_add_u64 v[142:143], v[186:187], 2, s[44:45]
	global_load_dwordx4 v[158:161], v[142:143], off nt
	global_load_dwordx4 v[180:183], v[142:143], off offset:16 nt
	v_lshlrev_b64 v[186:187], 1, v[186:187]
	v_cvt_pk_bf16_f32 v126, v126, v127
	v_cvt_pk_bf16_f32 v127, v128, v129
	v_cvt_pk_bf16_f32 v128, v122, v123
	v_cvt_pk_bf16_f32 v129, v124, v125
	v_lshl_add_u64 v[122:123], s[90:91], 0, v[186:187]
	global_store_dwordx4 v[122:123], v[126:129], off
	v_lshlrev_b32_e32 v124, 16, v128
	v_and_b32_e32 v125, 0xffff0000, v128
	v_lshlrev_b32_e32 v122, 16, v129
	v_and_b32_e32 v123, 0xffff0000, v129
	v_lshlrev_b32_e32 v128, 16, v126
	v_and_b32_e32 v129, 0xffff0000, v126
	v_lshlrev_b32_e32 v126, 16, v127
	v_and_b32_e32 v127, 0xffff0000, v127
	s_waitcnt vmcnt(2)
;     __device__ __forceinline__ void operator()(const f32x4 (&acc)[2][2][4][2], const Unit& u, int wr, int wc, int fr, int fq) const {
;     ...
;         for (int bj = 0; bj < 2; ++bj) {
;             const f32x4 g0 = gv[bj][0], g1 = gv[bj][1], G0 = Gv[bj][0], G1 = Gv[bj][1];
; #pragma unroll
;             for (int ai = 0; ai < 2; ++ai)
; #pragma unroll
;                 for (int m = 0; m < 4; ++m) { const size_t off = (size_t)(row0 + ai * HALF + m * 16) * 2048 + col0 + bj * HALF;
;                     f32x4 x0 = __builtin_nontemporal_load((const f32x4*)(base + off)), x1 = __builtin_nontemporal_load((const f32x4*)(base + off + 4));
;                     if constexpr (HAS_DIN) { const u32x4 dw = __builtin_nontemporal_load((const u32x4*)(dbuf + off));
;                         x0 += (f32x4){__builtin_bit_cast(float, dw.x << 16), __builtin_bit_cast(float, dw.x & 0xffff0000u), __builtin_bit_cast(float, dw.y << 16), __builtin_bit_cast(float, dw.y & 0xffff0000u)};
;                         x1 += (f32x4){__builtin_bit_cast(float, dw.z << 16), __builtin_bit_cast(float, dw.z & 0xffff0000u), __builtin_bit_cast(float, dw.w << 16), __builtin_bit_cast(float, dw.w & 0xffff0000u)}; }
;                     f32x4 o0, o1;
;                     if constexpr (OUT_DELTA) { const f32x4 d0 = g0 * acc[ai][bj][m][0], d1 = g1 * acc[ai][bj][m][1];
;                         u32x4 w; w.x = cvt_pk_bf16(d0[0], d0[1]); w.y = cvt_pk_bf16(d0[2], d0[3]); w.z = cvt_pk_bf16(d1[0], d1[1]); w.w = cvt_pk_bf16(d1[2], d1[3]);
;                         *(u32x4*)(dbuf + off) = w;
;                         o0 = x0 + (f32x4){__builtin_bit_cast(float, w.x << 16), __builtin_bit_cast(float, w.x & 0xffff0000u), __builtin_bit_cast(float, w.y << 16), __builtin_bit_cast(float, w.y & 0xffff0000u)};
;                         o1 = x1 + (f32x4){__builtin_bit_cast(float, w.z << 16), __builtin_bit_cast(float, w.z & 0xffff0000u), __builtin_bit_cast(float, w.w << 16), __builtin_bit_cast(float, w.w & 0xffff0000u)}; }
;                     else { o0 = x0 + g0 * acc[ai][bj][m][0]; o1 = x1 + g1 * acc[ai][bj][m][1]; *(f32x4*)(out + off) = o0; *(f32x4*)(out + off + 4) = o1; }
;                     if (Hn) { const f32x4 h0 = o0 * G0, h1 = o1 * G1;
;                         u32x4 w; w.x = cvt_pk_bf16(h0[0], h0[1]); w.y = cvt_pk_bf16(h0[2], h0[3]); w.z = cvt_pk_bf16(h1[0], h1[1]); w.w = cvt_pk_bf16(h1[2], h1[3]);
	v_pk_add_f32 v[126:127], v[160:161], v[126:127]
	s_waitcnt vmcnt(1)
	v_pk_add_f32 v[122:123], v[182:183], v[122:123]
	v_pk_add_f32 v[128:129], v[158:159], v[128:129]
	v_pk_add_f32 v[124:125], v[180:181], v[124:125]
	v_pk_mul_f32 v[160:161], v[198:199], v[126:127]
	v_pk_mul_f32 v[158:159], v[200:201], v[128:129]
	v_pk_mul_f32 v[180:181], v[202:203], v[122:123]
	v_pk_mul_f32 v[182:183], v[204:205], v[124:125]
	v_cvt_pk_bf16_f32 v158, v158, v159
	v_cvt_pk_bf16_f32 v159, v160, v161
	s_nop 0
	v_cvt_pk_bf16_f32 v160, v182, v183
	v_cvt_pk_bf16_f32 v161, v180, v181
	v_lshl_add_u64 v[180:181], s[96:97], 0, v[186:187]
	global_store_dwordx4 v[180:181], v[158:161], off
	s_nop 1
	v_or_b32_e32 v158, 48, v146
	v_ashrrev_i32_e32 v159, 31, v158
	v_lshlrev_b64 v[160:161], 11, v[158:159]
	v_lshl_add_u64 v[190:191], v[160:161], 0, v[148:149]
	v_lshl_add_u64 v[158:159], v[190:191], 2, s[44:45]
	global_load_dwordx4 v[180:183], v[158:159], off nt
	global_load_dwordx4 v[186:189], v[158:159], off offset:16 nt
	v_lshlrev_b64 v[190:191], 1, v[190:191]
	v_cvt_pk_bf16_f32 v118, v118, v119
	v_cvt_pk_bf16_f32 v119, v120, v121
	v_cvt_pk_bf16_f32 v120, v114, v115
	v_cvt_pk_bf16_f32 v121, v116, v117
	v_lshl_add_u64 v[114:115], s[90:91], 0, v[190:191]
	global_store_dwordx4 v[114:115], v[118:121], off
	v_lshlrev_b32_e32 v116, 16, v120
	v_and_b32_e32 v117, 0xffff0000, v120
	v_lshlrev_b32_e32 v114, 16, v121
	v_and_b32_e32 v115, 0xffff0000, v121
	v_lshlrev_b32_e32 v120, 16, v118
	v_and_b32_e32 v121, 0xffff0000, v118
	v_lshlrev_b32_e32 v118, 16, v119
	v_and_b32_e32 v119, 0xffff0000, v119
	s_waitcnt vmcnt(2)
	v_pk_add_f32 v[118:119], v[182:183], v[118:119]
	s_waitcnt vmcnt(1)
	v_pk_add_f32 v[114:115], v[188:189], v[114:115]
	v_pk_add_f32 v[120:121], v[180:181], v[120:121]
	v_pk_add_f32 v[116:117], v[186:187], v[116:117]
	v_pk_mul_f32 v[182:183], v[198:199], v[118:119]
	v_pk_mul_f32 v[180:181], v[200:201], v[120:121]
	v_pk_mul_f32 v[186:187], v[202:203], v[114:115]
	v_pk_mul_f32 v[188:189], v[204:205], v[116:117]
	v_cvt_pk_bf16_f32 v180, v180, v181
	v_cvt_pk_bf16_f32 v181, v182, v183
	s_nop 0
	v_cvt_pk_bf16_f32 v182, v188, v189
	v_cvt_pk_bf16_f32 v183, v186, v187
	v_lshl_add_u64 v[186:187], s[96:97], 0, v[190:191]
	global_store_dwordx4 v[186:187], v[180:183], off
	s_nop 1
	v_lshl_add_u64 v[182:183], v[184:185], 0, s[4:5]
	v_lshl_add_u64 v[194:195], v[182:183], 0, v[148:149]
	v_lshl_add_u64 v[180:181], v[194:195], 2, s[44:45]
	global_load_dwordx4 v[186:189], v[180:181], off nt
	global_load_dwordx4 v[190:193], v[180:181], off offset:16 nt
	v_lshlrev_b64 v[194:195], 1, v[194:195]
	v_cvt_pk_bf16_f32 v110, v110, v111
	v_cvt_pk_bf16_f32 v111, v112, v113
	v_cvt_pk_bf16_f32 v112, v106, v107
	v_cvt_pk_bf16_f32 v113, v108, v109
	v_lshl_add_u64 v[106:107], s[90:91], 0, v[194:195]
	global_store_dwordx4 v[106:107], v[110:113], off
	v_lshlrev_b32_e32 v108, 16, v112
	v_and_b32_e32 v109, 0xffff0000, v112
	v_lshlrev_b32_e32 v106, 16, v113
	v_and_b32_e32 v107, 0xffff0000, v113
	v_lshlrev_b32_e32 v112, 16, v110
	v_and_b32_e32 v113, 0xffff0000, v110
	v_lshlrev_b32_e32 v110, 16, v111
	v_and_b32_e32 v111, 0xffff0000, v111
	s_mov_b64 s[4:5], 0x48000
	s_waitcnt vmcnt(2)
	v_pk_add_f32 v[110:111], v[188:189], v[110:111]
	s_waitcnt vmcnt(1)
	v_pk_add_f32 v[106:107], v[192:193], v[106:107]
	v_pk_add_f32 v[112:113], v[186:187], v[112:113]
	v_pk_add_f32 v[108:109], v[190:191], v[108:109]
	v_pk_mul_f32 v[188:189], v[198:199], v[110:111]
	v_pk_mul_f32 v[186:187], v[200:201], v[112:113]
	v_pk_mul_f32 v[190:191], v[202:203], v[106:107]
	v_pk_mul_f32 v[192:193], v[204:205], v[108:109]
	v_cvt_pk_bf16_f32 v186, v186, v187
	v_cvt_pk_bf16_f32 v187, v188, v189
	s_nop 0
	v_cvt_pk_bf16_f32 v188, v192, v193
	v_cvt_pk_bf16_f32 v189, v190, v191
	v_lshl_add_u64 v[190:191], s[96:97], 0, v[194:195]
	global_store_dwordx4 v[190:191], v[186:189], off
	s_nop 1
	v_lshl_add_u64 v[188:189], v[184:185], 0, s[4:5]
	v_lshl_add_u64 v[212:213], v[188:189], 0, v[148:149]
	v_lshl_add_u64 v[186:187], v[212:213], 2, s[44:45]
	global_load_dwordx4 v[190:193], v[186:187], off nt
	global_load_dwordx4 v[194:197], v[186:187], off offset:16 nt
	v_lshlrev_b64 v[212:213], 1, v[212:213]
	v_cvt_pk_bf16_f32 v94, v94, v95
	v_cvt_pk_bf16_f32 v95, v96, v97
	v_cvt_pk_bf16_f32 v96, v90, v91
	v_cvt_pk_bf16_f32 v97, v92, v93
	v_lshl_add_u64 v[90:91], s[90:91], 0, v[212:213]
	global_store_dwordx4 v[90:91], v[94:97], off
	v_lshlrev_b32_e32 v92, 16, v96
	v_and_b32_e32 v93, 0xffff0000, v96
	v_lshlrev_b32_e32 v90, 16, v97
	v_and_b32_e32 v91, 0xffff0000, v97
	v_lshlrev_b32_e32 v96, 16, v94
	v_and_b32_e32 v97, 0xffff0000, v94
	v_lshlrev_b32_e32 v94, 16, v95
	v_and_b32_e32 v95, 0xffff0000, v95
	s_mov_b64 s[4:5], 0x50000
	s_waitcnt vmcnt(2)
	v_pk_add_f32 v[94:95], v[192:193], v[94:95]
	s_waitcnt vmcnt(1)
	v_pk_add_f32 v[90:91], v[196:197], v[90:91]
	v_pk_add_f32 v[96:97], v[190:191], v[96:97]
	v_pk_add_f32 v[92:93], v[194:195], v[92:93]
	v_pk_mul_f32 v[192:193], v[198:199], v[94:95]
	v_pk_mul_f32 v[190:191], v[200:201], v[96:97]
	v_pk_mul_f32 v[194:195], v[202:203], v[90:91]
	v_pk_mul_f32 v[196:197], v[204:205], v[92:93]
	v_cvt_pk_bf16_f32 v190, v190, v191
	v_cvt_pk_bf16_f32 v191, v192, v193
	s_nop 0
	v_cvt_pk_bf16_f32 v192, v196, v197
	v_cvt_pk_bf16_f32 v193, v194, v195
	v_lshl_add_u64 v[194:195], s[96:97], 0, v[212:213]
	global_store_dwordx4 v[194:195], v[190:193], off
	s_nop 1
	v_lshl_add_u64 v[192:193], v[184:185], 0, s[4:5]
	v_lshl_add_u64 v[220:221], v[192:193], 0, v[148:149]
	v_lshl_add_u64 v[190:191], v[220:221], 2, s[44:45]
	global_load_dwordx4 v[194:197], v[190:191], off nt
	global_load_dwordx4 v[212:215], v[190:191], off offset:16 nt
	v_lshlrev_b64 v[220:221], 1, v[220:221]
	v_cvt_pk_bf16_f32 v86, v86, v87
	v_cvt_pk_bf16_f32 v87, v88, v89
	v_cvt_pk_bf16_f32 v88, v82, v83
	v_cvt_pk_bf16_f32 v89, v84, v85
	v_lshl_add_u64 v[82:83], s[90:91], 0, v[220:221]
	global_store_dwordx4 v[82:83], v[86:89], off
	v_lshlrev_b32_e32 v84, 16, v88
	v_and_b32_e32 v85, 0xffff0000, v88
	v_lshlrev_b32_e32 v82, 16, v89
	v_and_b32_e32 v83, 0xffff0000, v89
	v_lshlrev_b32_e32 v88, 16, v86
	v_and_b32_e32 v89, 0xffff0000, v86
	v_lshlrev_b32_e32 v86, 16, v87
	v_and_b32_e32 v87, 0xffff0000, v87
	s_mov_b64 s[4:5], 0x58000
	s_waitcnt vmcnt(2)
;     __device__ __forceinline__ void operator()(const f32x4 (&acc)[2][2][4][2], const Unit& u, int wr, int wc, int fr, int fq) const {
;     ...
;         for (int bj = 0; bj < 2; ++bj) {
;             const f32x4 g0 = gv[bj][0], g1 = gv[bj][1], G0 = Gv[bj][0], G1 = Gv[bj][1];
; #pragma unroll
;             for (int ai = 0; ai < 2; ++ai)
; #pragma unroll
;                 for (int m = 0; m < 4; ++m) { const size_t off = (size_t)(row0 + ai * HALF + m * 16) * 2048 + col0 + bj * HALF;
;                     f32x4 x0 = __builtin_nontemporal_load((const f32x4*)(base + off)), x1 = __builtin_nontemporal_load((const f32x4*)(base + off + 4));
;                     if constexpr (HAS_DIN) { const u32x4 dw = __builtin_nontemporal_load((const u32x4*)(dbuf + off));
;                         x0 += (f32x4){__builtin_bit_cast(float, dw.x << 16), __builtin_bit_cast(float, dw.x & 0xffff0000u), __builtin_bit_cast(float, dw.y << 16), __builtin_bit_cast(float, dw.y & 0xffff0000u)};
;                         x1 += (f32x4){__builtin_bit_cast(float, dw.z << 16), __builtin_bit_cast(float, dw.z & 0xffff0000u), __builtin_bit_cast(float, dw.w << 16), __builtin_bit_cast(float, dw.w & 0xffff0000u)}; }
;                     f32x4 o0, o1;
;                     if constexpr (OUT_DELTA) { const f32x4 d0 = g0 * acc[ai][bj][m][0], d1 = g1 * acc[ai][bj][m][1];
;                         u32x4 w; w.x = cvt_pk_bf16(d0[0], d0[1]); w.y = cvt_pk_bf16(d0[2], d0[3]); w.z = cvt_pk_bf16(d1[0], d1[1]); w.w = cvt_pk_bf16(d1[2], d1[3]);
;                         *(u32x4*)(dbuf + off) = w;
;                         o0 = x0 + (f32x4){__builtin_bit_cast(float, w.x << 16), __builtin_bit_cast(float, w.x & 0xffff0000u), __builtin_bit_cast(float, w.y << 16), __builtin_bit_cast(float, w.y & 0xffff0000u)};
;                         o1 = x1 + (f32x4){__builtin_bit_cast(float, w.z << 16), __builtin_bit_cast(float, w.z & 0xffff0000u), __builtin_bit_cast(float, w.w << 16), __builtin_bit_cast(float, w.w & 0xffff0000u)}; }
;                     else { o0 = x0 + g0 * acc[ai][bj][m][0]; o1 = x1 + g1 * acc[ai][bj][m][1]; *(f32x4*)(out + off) = o0; *(f32x4*)(out + off + 4) = o1; }
;                     if (Hn) { const f32x4 h0 = o0 * G0, h1 = o1 * G1;
;                         u32x4 w; w.x = cvt_pk_bf16(h0[0], h0[1]); w.y = cvt_pk_bf16(h0[2], h0[3]); w.z = cvt_pk_bf16(h1[0], h1[1]); w.w = cvt_pk_bf16(h1[2], h1[3]);
	v_pk_add_f32 v[86:87], v[196:197], v[86:87]
	s_waitcnt vmcnt(1)
	v_pk_add_f32 v[82:83], v[214:215], v[82:83]
	v_pk_add_f32 v[88:89], v[194:195], v[88:89]
	v_pk_add_f32 v[84:85], v[212:213], v[84:85]
	v_pk_mul_f32 v[196:197], v[198:199], v[86:87]
	v_pk_mul_f32 v[194:195], v[200:201], v[88:89]
	v_pk_mul_f32 v[212:213], v[202:203], v[82:83]
	v_pk_mul_f32 v[214:215], v[204:205], v[84:85]
	v_cvt_pk_bf16_f32 v194, v194, v195
	v_cvt_pk_bf16_f32 v195, v196, v197
	s_nop 0
	v_cvt_pk_bf16_f32 v196, v214, v215
	v_cvt_pk_bf16_f32 v197, v212, v213
	v_lshl_add_u64 v[212:213], s[96:97], 0, v[220:221]
	global_store_dwordx4 v[212:213], v[194:197], off
	s_nop 1
	v_lshl_add_u64 v[196:197], v[184:185], 0, s[4:5]
	v_lshl_add_u64 v[224:225], v[196:197], 0, v[148:149]
	v_lshl_add_u64 v[194:195], v[224:225], 2, s[44:45]
	global_load_dwordx4 v[212:215], v[194:195], off nt
	global_load_dwordx4 v[220:223], v[194:195], off offset:16 nt
	v_lshlrev_b64 v[102:103], 1, v[224:225]
	v_cvt_pk_bf16_f32 v78, v78, v79
	v_cvt_pk_bf16_f32 v79, v80, v81
	v_cvt_pk_bf16_f32 v80, v74, v75
	v_cvt_pk_bf16_f32 v81, v76, v77
	v_lshl_add_u64 v[74:75], s[90:91], 0, v[102:103]
	global_store_dwordx4 v[74:75], v[78:81], off
	v_lshlrev_b32_e32 v76, 16, v80
	v_and_b32_e32 v77, 0xffff0000, v80
	v_lshlrev_b32_e32 v74, 16, v81
	v_and_b32_e32 v75, 0xffff0000, v81
	v_lshlrev_b32_e32 v80, 16, v78
	v_and_b32_e32 v81, 0xffff0000, v78
	v_lshlrev_b32_e32 v78, 16, v79
	v_and_b32_e32 v79, 0xffff0000, v79
	v_lshl_add_u64 v[102:103], s[96:97], 0, v[102:103]
	v_or_b32_e32 v148, 0x80, v148
	s_waitcnt vmcnt(2)
	v_pk_add_f32 v[78:79], v[214:215], v[78:79]
	v_pk_add_f32 v[80:81], v[212:213], v[80:81]
	s_waitcnt vmcnt(1)
	v_pk_add_f32 v[74:75], v[222:223], v[74:75]
	v_pk_add_f32 v[76:77], v[220:221], v[76:77]
	v_pk_mul_f32 v[100:101], v[198:199], v[78:79]
	v_pk_mul_f32 v[98:99], v[200:201], v[80:81]
	v_pk_mul_f32 v[104:105], v[202:203], v[74:75]
	v_pk_mul_f32 v[198:199], v[204:205], v[76:77]
	v_cvt_pk_bf16_f32 v98, v98, v99
	v_cvt_pk_bf16_f32 v99, v100, v101
	s_nop 0
	v_cvt_pk_bf16_f32 v100, v198, v199
	v_cvt_pk_bf16_f32 v101, v104, v105
	global_store_dwordx4 v[102:103], v[98:101], off
	global_load_dwordx4 v[100:103], v[178:179], off offset:512 nt
	global_load_dwordx4 v[198:201], v[178:179], off offset:528 nt
	v_lshl_add_u64 v[98:99], v[184:185], 0, v[148:149]
	v_pk_mul_f32 v[104:105], v[68:69], v[28:29]
	v_pk_mul_f32 v[68:69], v[66:67], v[26:27]
	v_cvt_pk_bf16_f32 v66, v70, v71
	v_cvt_pk_bf16_f32 v67, v72, v73
	s_nop 0
	v_cvt_pk_bf16_f32 v68, v68, v69
	v_cvt_pk_bf16_f32 v69, v104, v105
	v_lshlrev_b64 v[104:105], 1, v[98:99]
	v_lshl_add_u64 v[70:71], s[90:91], 0, v[104:105]
	global_store_dwordx4 v[70:71], v[66:69], off
	v_lshlrev_b32_e32 v72, 16, v68
	v_and_b32_e32 v73, 0xffff0000, v68
	v_lshlrev_b32_e32 v68, 16, v69
	v_and_b32_e32 v69, 0xffff0000, v69
	s_waitcnt vmcnt(1)
	v_pk_add_f32 v[70:71], v[200:201], v[68:69]
	v_lshlrev_b32_e32 v68, 16, v66
	v_and_b32_e32 v69, 0xffff0000, v66
	v_lshlrev_b32_e32 v66, 16, v67
	v_and_b32_e32 v67, 0xffff0000, v67
	v_pk_add_f32 v[98:99], v[102:103], v[66:67]
	v_pk_add_f32 v[100:101], v[100:101], v[68:69]
	v_pk_add_f32 v[72:73], v[198:199], v[72:73]
	v_pk_mul_f32 v[68:69], v[150:151], v[98:99]
	v_pk_mul_f32 v[66:67], v[152:153], v[100:101]
	v_pk_mul_f32 v[102:103], v[154:155], v[70:71]
	v_pk_mul_f32 v[178:179], v[156:157], v[72:73]
	v_cvt_pk_bf16_f32 v66, v66, v67
	v_cvt_pk_bf16_f32 v67, v68, v69
	s_nop 0
	v_cvt_pk_bf16_f32 v68, v178, v179
	v_cvt_pk_bf16_f32 v69, v102, v103
	v_lshl_add_u64 v[102:103], s[96:97], 0, v[104:105]
	global_store_dwordx4 v[102:103], v[66:69], off
	s_nop 1
	v_mul_f32_e32 v66, v101, v101
	v_mul_f32_e32 v67, v99, v99
	v_fmac_f32_e32 v66, v100, v100
	v_fmac_f32_e32 v67, v98, v98
	v_add_f32_e32 v66, v66, v67
	v_mul_f32_e32 v67, v73, v73
	v_mul_f32_e32 v68, v71, v71
	v_fmac_f32_e32 v67, v72, v72
	v_fmac_f32_e32 v68, v70, v70
	v_add_f32_e32 v67, v67, v68
	global_load_dwordx4 v[68:71], v[138:139], off offset:512 nt
	global_load_dwordx4 v[98:101], v[138:139], off offset:528 nt
	v_lshl_add_u64 v[72:73], v[140:141], 0, v[148:149]
	v_lshlrev_b64 v[72:73], 1, v[72:73]
	v_cvt_pk_bf16_f32 v62, v62, v63
	v_cvt_pk_bf16_f32 v63, v64, v65
	v_cvt_pk_bf16_f32 v64, v58, v59
	v_cvt_pk_bf16_f32 v65, v60, v61
	v_lshl_add_u64 v[58:59], s[90:91], 0, v[72:73]
	global_store_dwordx4 v[58:59], v[62:65], off
	v_lshlrev_b32_e32 v60, 16, v64
	v_and_b32_e32 v61, 0xffff0000, v64
	v_lshlrev_b32_e32 v58, 16, v65
	v_and_b32_e32 v59, 0xffff0000, v65
	v_lshlrev_b32_e32 v64, 16, v62
	v_and_b32_e32 v65, 0xffff0000, v62
	v_lshlrev_b32_e32 v62, 16, v63
	v_and_b32_e32 v63, 0xffff0000, v63
	v_lshl_add_u64 v[72:73], s[96:97], 0, v[72:73]
	v_add_f32_e32 v66, v66, v67
	v_add_f32_e32 v66, v211, v66
	s_waitcnt vmcnt(2)
	v_pk_add_f32 v[62:63], v[70:71], v[62:63]
	v_pk_add_f32 v[64:65], v[68:69], v[64:65]
	s_waitcnt vmcnt(1)
	v_pk_add_f32 v[58:59], v[100:101], v[58:59]
	v_pk_add_f32 v[60:61], v[98:99], v[60:61]
	v_pk_mul_f32 v[70:71], v[150:151], v[62:63]
	v_pk_mul_f32 v[68:69], v[152:153], v[64:65]
	v_pk_mul_f32 v[98:99], v[154:155], v[58:59]
	v_pk_mul_f32 v[100:101], v[156:157], v[60:61]
	v_cvt_pk_bf16_f32 v68, v68, v69
	v_cvt_pk_bf16_f32 v69, v70, v71
	s_nop 0
	v_cvt_pk_bf16_f32 v70, v100, v101
	v_cvt_pk_bf16_f32 v71, v98, v99
	global_store_dwordx4 v[72:73], v[68:71], off
	global_load_dwordx4 v[68:71], v[142:143], off offset:512 nt
	s_nop 0
	global_load_dwordx4 v[98:101], v[142:143], off offset:528 nt
	v_lshl_add_u64 v[72:73], v[144:145], 0, v[148:149]
	v_lshlrev_b64 v[72:73], 1, v[72:73]
	v_cvt_pk_bf16_f32 v54, v54, v55
	v_cvt_pk_bf16_f32 v55, v56, v57
	v_cvt_pk_bf16_f32 v56, v50, v51
	v_cvt_pk_bf16_f32 v57, v52, v53
	v_lshl_add_u64 v[50:51], s[90:91], 0, v[72:73]
	global_store_dwordx4 v[50:51], v[54:57], off
	v_lshlrev_b32_e32 v52, 16, v56
	v_and_b32_e32 v53, 0xffff0000, v56
	v_lshlrev_b32_e32 v50, 16, v57
	v_and_b32_e32 v51, 0xffff0000, v57
	v_lshlrev_b32_e32 v56, 16, v54
	v_and_b32_e32 v57, 0xffff0000, v54
	v_lshlrev_b32_e32 v54, 16, v55
	v_and_b32_e32 v55, 0xffff0000, v55
	v_lshl_add_u64 v[72:73], s[96:97], 0, v[72:73]
	s_waitcnt vmcnt(2)
;     __device__ __forceinline__ void operator()(const f32x4 (&acc)[2][2][4][2], const Unit& u, int wr, int wc, int fr, int fq) const {
;     ...
;         for (int bj = 0; bj < 2; ++bj) {
;             const f32x4 g0 = gv[bj][0], g1 = gv[bj][1], G0 = Gv[bj][0], G1 = Gv[bj][1];
; #pragma unroll
;             for (int ai = 0; ai < 2; ++ai)
; #pragma unroll
;                 for (int m = 0; m < 4; ++m) { const size_t off = (size_t)(row0 + ai * HALF + m * 16) * 2048 + col0 + bj * HALF;
;                     f32x4 x0 = __builtin_nontemporal_load((const f32x4*)(base + off)), x1 = __builtin_nontemporal_load((const f32x4*)(base + off + 4));
;                     if constexpr (HAS_DIN) { const u32x4 dw = __builtin_nontemporal_load((const u32x4*)(dbuf + off));
;                         x0 += (f32x4){__builtin_bit_cast(float, dw.x << 16), __builtin_bit_cast(float, dw.x & 0xffff0000u), __builtin_bit_cast(float, dw.y << 16), __builtin_bit_cast(float, dw.y & 0xffff0000u)};
;                         x1 += (f32x4){__builtin_bit_cast(float, dw.z << 16), __builtin_bit_cast(float, dw.z & 0xffff0000u), __builtin_bit_cast(float, dw.w << 16), __builtin_bit_cast(float, dw.w & 0xffff0000u)}; }
;                     f32x4 o0, o1;
;                     if constexpr (OUT_DELTA) { const f32x4 d0 = g0 * acc[ai][bj][m][0], d1 = g1 * acc[ai][bj][m][1];
;                         u32x4 w; w.x = cvt_pk_bf16(d0[0], d0[1]); w.y = cvt_pk_bf16(d0[2], d0[3]); w.z = cvt_pk_bf16(d1[0], d1[1]); w.w = cvt_pk_bf16(d1[2], d1[3]);
;                         *(u32x4*)(dbuf + off) = w;
;                         o0 = x0 + (f32x4){__builtin_bit_cast(float, w.x << 16), __builtin_bit_cast(float, w.x & 0xffff0000u), __builtin_bit_cast(float, w.y << 16), __builtin_bit_cast(float, w.y & 0xffff0000u)};
;                         o1 = x1 + (f32x4){__builtin_bit_cast(float, w.z << 16), __builtin_bit_cast(float, w.z & 0xffff0000u), __builtin_bit_cast(float, w.w << 16), __builtin_bit_cast(float, w.w & 0xffff0000u)}; }
;                     else { o0 = x0 + g0 * acc[ai][bj][m][0]; o1 = x1 + g1 * acc[ai][bj][m][1]; *(f32x4*)(out + off) = o0; *(f32x4*)(out + off + 4) = o1; }
;                     if (Hn) { const f32x4 h0 = o0 * G0, h1 = o1 * G1;
;                         u32x4 w; w.x = cvt_pk_bf16(h0[0], h0[1]); w.y = cvt_pk_bf16(h0[2], h0[3]); w.z = cvt_pk_bf16(h1[0], h1[1]); w.w = cvt_pk_bf16(h1[2], h1[3]);
	v_pk_add_f32 v[54:55], v[70:71], v[54:55]
	v_pk_add_f32 v[56:57], v[68:69], v[56:57]
	s_waitcnt vmcnt(1)
	v_pk_add_f32 v[50:51], v[100:101], v[50:51]
	v_pk_add_f32 v[52:53], v[98:99], v[52:53]
	v_pk_mul_f32 v[70:71], v[150:151], v[54:55]
	v_pk_mul_f32 v[68:69], v[152:153], v[56:57]
	v_pk_mul_f32 v[98:99], v[154:155], v[50:51]
	v_pk_mul_f32 v[100:101], v[156:157], v[52:53]
	v_cvt_pk_bf16_f32 v68, v68, v69
	v_cvt_pk_bf16_f32 v69, v70, v71
	s_nop 0
	v_cvt_pk_bf16_f32 v70, v100, v101
	v_cvt_pk_bf16_f32 v71, v98, v99
	global_store_dwordx4 v[72:73], v[68:71], off
	global_load_dwordx4 v[68:71], v[158:159], off offset:512 nt
	s_nop 0
	global_load_dwordx4 v[98:101], v[158:159], off offset:528 nt
	v_lshl_add_u64 v[72:73], v[160:161], 0, v[148:149]
	v_lshlrev_b64 v[72:73], 1, v[72:73]
	v_cvt_pk_bf16_f32 v46, v46, v47
	v_cvt_pk_bf16_f32 v47, v48, v49
	v_cvt_pk_bf16_f32 v48, v42, v43
	v_cvt_pk_bf16_f32 v49, v44, v45
	v_lshl_add_u64 v[42:43], s[90:91], 0, v[72:73]
	global_store_dwordx4 v[42:43], v[46:49], off
	v_lshlrev_b32_e32 v44, 16, v48
	v_and_b32_e32 v45, 0xffff0000, v48
	v_lshlrev_b32_e32 v42, 16, v49
	v_and_b32_e32 v43, 0xffff0000, v49
	v_lshlrev_b32_e32 v48, 16, v46
	v_and_b32_e32 v49, 0xffff0000, v46
	v_lshlrev_b32_e32 v46, 16, v47
	v_and_b32_e32 v47, 0xffff0000, v47
	v_lshl_add_u64 v[72:73], s[96:97], 0, v[72:73]
	s_waitcnt vmcnt(2)
	v_pk_add_f32 v[46:47], v[70:71], v[46:47]
	v_pk_add_f32 v[48:49], v[68:69], v[48:49]
	s_waitcnt vmcnt(1)
	v_pk_add_f32 v[42:43], v[100:101], v[42:43]
	v_pk_add_f32 v[44:45], v[98:99], v[44:45]
	v_pk_mul_f32 v[70:71], v[150:151], v[46:47]
	v_pk_mul_f32 v[68:69], v[152:153], v[48:49]
	v_pk_mul_f32 v[98:99], v[154:155], v[42:43]
	v_pk_mul_f32 v[100:101], v[156:157], v[44:45]
	v_cvt_pk_bf16_f32 v68, v68, v69
	v_cvt_pk_bf16_f32 v69, v70, v71
	s_nop 0
	v_cvt_pk_bf16_f32 v70, v100, v101
	v_cvt_pk_bf16_f32 v71, v98, v99
	global_store_dwordx4 v[72:73], v[68:71], off
	global_load_dwordx4 v[68:71], v[180:181], off offset:512 nt
	s_nop 0
	global_load_dwordx4 v[98:101], v[180:181], off offset:528 nt
	v_lshl_add_u64 v[72:73], v[182:183], 0, v[148:149]
	v_lshlrev_b64 v[72:73], 1, v[72:73]
	v_cvt_pk_bf16_f32 v38, v38, v39
	v_cvt_pk_bf16_f32 v39, v40, v41
	v_cvt_pk_bf16_f32 v40, v34, v35
	v_cvt_pk_bf16_f32 v41, v36, v37
	v_lshl_add_u64 v[34:35], s[90:91], 0, v[72:73]
	global_store_dwordx4 v[34:35], v[38:41], off
	v_lshlrev_b32_e32 v36, 16, v40
	v_and_b32_e32 v37, 0xffff0000, v40
	v_lshlrev_b32_e32 v34, 16, v41
	v_and_b32_e32 v35, 0xffff0000, v41
	v_lshlrev_b32_e32 v40, 16, v38
	v_and_b32_e32 v41, 0xffff0000, v38
	v_lshlrev_b32_e32 v38, 16, v39
	v_and_b32_e32 v39, 0xffff0000, v39
	v_lshl_add_u64 v[72:73], s[96:97], 0, v[72:73]
	s_waitcnt vmcnt(2)
	v_pk_add_f32 v[38:39], v[70:71], v[38:39]
	v_pk_add_f32 v[40:41], v[68:69], v[40:41]
	s_waitcnt vmcnt(1)
	v_pk_add_f32 v[34:35], v[100:101], v[34:35]
	v_pk_add_f32 v[36:37], v[98:99], v[36:37]
	v_pk_mul_f32 v[70:71], v[150:151], v[38:39]
	v_pk_mul_f32 v[68:69], v[152:153], v[40:41]
	v_pk_mul_f32 v[98:99], v[154:155], v[34:35]
	v_pk_mul_f32 v[100:101], v[156:157], v[36:37]
	v_cvt_pk_bf16_f32 v68, v68, v69
	v_cvt_pk_bf16_f32 v69, v70, v71
	s_nop 0
	v_cvt_pk_bf16_f32 v70, v100, v101
	v_cvt_pk_bf16_f32 v71, v98, v99
	global_store_dwordx4 v[72:73], v[68:71], off
	global_load_dwordx4 v[68:71], v[186:187], off offset:512 nt
	s_nop 0
	global_load_dwordx4 v[98:101], v[186:187], off offset:528 nt
	v_lshl_add_u64 v[72:73], v[188:189], 0, v[148:149]
	v_lshlrev_b64 v[72:73], 1, v[72:73]
	v_cvt_pk_bf16_f32 v22, v22, v23
	v_cvt_pk_bf16_f32 v23, v24, v25
	v_cvt_pk_bf16_f32 v24, v18, v19
	v_cvt_pk_bf16_f32 v25, v20, v21
	v_lshl_add_u64 v[18:19], s[90:91], 0, v[72:73]
	global_store_dwordx4 v[18:19], v[22:25], off
	v_lshlrev_b32_e32 v20, 16, v24
	v_and_b32_e32 v21, 0xffff0000, v24
	v_lshlrev_b32_e32 v18, 16, v25
	v_and_b32_e32 v19, 0xffff0000, v25
	v_lshlrev_b32_e32 v24, 16, v22
	v_and_b32_e32 v25, 0xffff0000, v22
	v_lshlrev_b32_e32 v22, 16, v23
	v_and_b32_e32 v23, 0xffff0000, v23
	v_lshl_add_u64 v[72:73], s[96:97], 0, v[72:73]
	s_waitcnt vmcnt(2)
	v_pk_add_f32 v[22:23], v[70:71], v[22:23]
	v_pk_add_f32 v[24:25], v[68:69], v[24:25]
	s_waitcnt vmcnt(1)
;     __device__ __forceinline__ void operator()(const f32x4 (&acc)[2][2][4][2], const Unit& u, int wr, int wc, int fr, int fq) const {
;     ...
;         for (int bj = 0; bj < 2; ++bj) {
;             const f32x4 g0 = gv[bj][0], g1 = gv[bj][1], G0 = Gv[bj][0], G1 = Gv[bj][1];
; #pragma unroll
;             for (int ai = 0; ai < 2; ++ai)
; #pragma unroll
;                 for (int m = 0; m < 4; ++m) { const size_t off = (size_t)(row0 + ai * HALF + m * 16) * 2048 + col0 + bj * HALF;
;                     f32x4 x0 = __builtin_nontemporal_load((const f32x4*)(base + off)), x1 = __builtin_nontemporal_load((const f32x4*)(base + off + 4));
;                     if constexpr (HAS_DIN) { const u32x4 dw = __builtin_nontemporal_load((const u32x4*)(dbuf + off));
;                         x0 += (f32x4){__builtin_bit_cast(float, dw.x << 16), __builtin_bit_cast(float, dw.x & 0xffff0000u), __builtin_bit_cast(float, dw.y << 16), __builtin_bit_cast(float, dw.y & 0xffff0000u)};
;                         x1 += (f32x4){__builtin_bit_cast(float, dw.z << 16), __builtin_bit_cast(float, dw.z & 0xffff0000u), __builtin_bit_cast(float, dw.w << 16), __builtin_bit_cast(float, dw.w & 0xffff0000u)}; }
;                     f32x4 o0, o1;
;                     if constexpr (OUT_DELTA) { const f32x4 d0 = g0 * acc[ai][bj][m][0], d1 = g1 * acc[ai][bj][m][1];
;                         u32x4 w; w.x = cvt_pk_bf16(d0[0], d0[1]); w.y = cvt_pk_bf16(d0[2], d0[3]); w.z = cvt_pk_bf16(d1[0], d1[1]); w.w = cvt_pk_bf16(d1[2], d1[3]);
;                         *(u32x4*)(dbuf + off) = w;
;                         o0 = x0 + (f32x4){__builtin_bit_cast(float, w.x << 16), __builtin_bit_cast(float, w.x & 0xffff0000u), __builtin_bit_cast(float, w.y << 16), __builtin_bit_cast(float, w.y & 0xffff0000u)};
;                         o1 = x1 + (f32x4){__builtin_bit_cast(float, w.z << 16), __builtin_bit_cast(float, w.z & 0xffff0000u), __builtin_bit_cast(float, w.w << 16), __builtin_bit_cast(float, w.w & 0xffff0000u)}; }
;                     else { o0 = x0 + g0 * acc[ai][bj][m][0]; o1 = x1 + g1 * acc[ai][bj][m][1]; *(f32x4*)(out + off) = o0; *(f32x4*)(out + off + 4) = o1; }
;                     if (Hn) { const f32x4 h0 = o0 * G0, h1 = o1 * G1;
;                         u32x4 w; w.x = cvt_pk_bf16(h0[0], h0[1]); w.y = cvt_pk_bf16(h0[2], h0[3]); w.z = cvt_pk_bf16(h1[0], h1[1]); w.w = cvt_pk_bf16(h1[2], h1[3]);
	v_pk_add_f32 v[18:19], v[100:101], v[18:19]
	v_pk_add_f32 v[20:21], v[98:99], v[20:21]
	v_pk_mul_f32 v[70:71], v[150:151], v[22:23]
	v_pk_mul_f32 v[68:69], v[152:153], v[24:25]
	v_pk_mul_f32 v[98:99], v[154:155], v[18:19]
	v_pk_mul_f32 v[100:101], v[156:157], v[20:21]
	v_cvt_pk_bf16_f32 v68, v68, v69
	v_cvt_pk_bf16_f32 v69, v70, v71
	s_nop 0
	v_cvt_pk_bf16_f32 v70, v100, v101
	v_cvt_pk_bf16_f32 v71, v98, v99
	global_store_dwordx4 v[72:73], v[68:71], off
	global_load_dwordx4 v[68:71], v[190:191], off offset:512 nt
	s_nop 0
	global_load_dwordx4 v[98:101], v[190:191], off offset:528 nt
	v_lshl_add_u64 v[72:73], v[192:193], 0, v[148:149]
	v_lshlrev_b64 v[72:73], 1, v[72:73]
	v_cvt_pk_bf16_f32 v14, v14, v15
	v_cvt_pk_bf16_f32 v15, v16, v17
	v_cvt_pk_bf16_f32 v16, v10, v11
	v_cvt_pk_bf16_f32 v17, v12, v13
	v_lshl_add_u64 v[10:11], s[90:91], 0, v[72:73]
	global_store_dwordx4 v[10:11], v[14:17], off
	v_lshlrev_b32_e32 v12, 16, v16
	v_and_b32_e32 v13, 0xffff0000, v16
	v_lshlrev_b32_e32 v10, 16, v17
	v_and_b32_e32 v11, 0xffff0000, v17
	v_lshlrev_b32_e32 v16, 16, v14
	v_and_b32_e32 v17, 0xffff0000, v14
	v_lshlrev_b32_e32 v14, 16, v15
	v_and_b32_e32 v15, 0xffff0000, v15
	v_lshl_add_u64 v[72:73], s[96:97], 0, v[72:73]
	s_waitcnt vmcnt(2)
	v_pk_add_f32 v[14:15], v[70:71], v[14:15]
	v_pk_add_f32 v[16:17], v[68:69], v[16:17]
	s_waitcnt vmcnt(1)
	v_pk_add_f32 v[10:11], v[100:101], v[10:11]
	v_pk_add_f32 v[12:13], v[98:99], v[12:13]
	v_pk_mul_f32 v[70:71], v[150:151], v[14:15]
	v_pk_mul_f32 v[68:69], v[152:153], v[16:17]
	v_pk_mul_f32 v[98:99], v[154:155], v[10:11]
	v_pk_mul_f32 v[100:101], v[156:157], v[12:13]
	v_cvt_pk_bf16_f32 v68, v68, v69
	v_cvt_pk_bf16_f32 v69, v70, v71
	s_nop 0
	v_cvt_pk_bf16_f32 v70, v100, v101
	v_cvt_pk_bf16_f32 v71, v98, v99
	global_store_dwordx4 v[72:73], v[68:71], off
	global_load_dwordx4 v[68:71], v[194:195], off offset:512 nt
	s_nop 0
	global_load_dwordx4 v[98:101], v[194:195], off offset:528 nt
	v_lshl_add_u64 v[72:73], v[196:197], 0, v[148:149]
	v_lshlrev_b64 v[30:31], 1, v[72:73]
	v_cvt_pk_bf16_f32 v6, v6, v7
	v_cvt_pk_bf16_f32 v7, v8, v9
	v_cvt_pk_bf16_f32 v8, v2, v3
	v_cvt_pk_bf16_f32 v9, v4, v5
	v_lshl_add_u64 v[2:3], s[90:91], 0, v[30:31]
	global_store_dwordx4 v[2:3], v[6:9], off
	v_lshlrev_b32_e32 v4, 16, v8
	v_and_b32_e32 v5, 0xffff0000, v8
	v_lshlrev_b32_e32 v2, 16, v9
	v_and_b32_e32 v3, 0xffff0000, v9
	v_lshlrev_b32_e32 v8, 16, v6
	v_and_b32_e32 v9, 0xffff0000, v6
	v_lshlrev_b32_e32 v6, 16, v7
	v_and_b32_e32 v7, 0xffff0000, v7
	v_lshl_add_u64 v[30:31], s[96:97], 0, v[30:31]
	s_waitcnt vmcnt(2)
	v_pk_add_f32 v[8:9], v[68:69], v[8:9]
	v_pk_add_f32 v[6:7], v[70:71], v[6:7]
	v_pk_mul_f32 v[26:27], v[152:153], v[8:9]
	s_waitcnt vmcnt(1)
	v_pk_add_f32 v[2:3], v[100:101], v[2:3]
	v_pk_add_f32 v[4:5], v[98:99], v[4:5]
	v_pk_mul_f32 v[28:29], v[150:151], v[6:7]
	v_cvt_pk_bf16_f32 v26, v26, v27
	v_pk_mul_f32 v[32:33], v[154:155], v[2:3]
	v_cvt_pk_bf16_f32 v27, v28, v29
	v_pk_mul_f32 v[68:69], v[156:157], v[4:5]
	s_nop 0
	v_cvt_pk_bf16_f32 v28, v68, v69
	v_cvt_pk_bf16_f32 v29, v32, v33
	global_store_dwordx4 v[30:31], v[26:29], off
	s_nop 1
	v_and_b32_e32 v27, 64, v218
	v_xor_b32_e32 v26, 16, v218
	v_add_u32_e32 v27, 64, v27
	v_cmp_lt_i32_e32 vcc, v26, v27
	s_nop 1
	v_cndmask_b32_e32 v26, v218, v26, vcc
	v_lshlrev_b32_e32 v28, 2, v26
	v_xor_b32_e32 v26, 32, v218
	v_cmp_lt_i32_e32 vcc, v26, v27
	s_nop 1
	v_cndmask_b32_e32 v26, v218, v26, vcc
	v_lshlrev_b32_e32 v29, 2, v26
	ds_bpermute_b32 v26, v28, v66
	s_waitcnt lgkmcnt(0)
	v_add_f32_e32 v30, v66, v26
	ds_bpermute_b32 v31, v29, v30
	v_lshl_add_u64 v[26:27], v[146:147], 3, s[42:43]
	s_and_saveexec_b64 s[4:5], s[0:1]
	s_mov_b32 s8, 0x2f800000
	s_mov_b32 s9, 0xcf800000
	s_cbranch_execz .LBB0_558
	s_waitcnt lgkmcnt(0)
	v_add_f32_e32 v30, v30, v31
	v_mul_f32_e32 v30, 0x47800000, v30
	v_rndne_f32_e32 v30, v30
	v_mul_f32_e64 v31, |v30|, s8
	v_floor_f32_e32 v31, v31
	v_fma_f32 v32, v31, s9, |v30|
	v_cvt_u32_f32_e32 v32, v32
	v_cvt_u32_f32_e32 v31, v31
	v_ashrrev_i32_e32 v33, 31, v30
	v_xor_b32_e32 v30, v32, v33
	v_xor_b32_e32 v31, v31, v33
	v_sub_co_u32_e32 v30, vcc, v30, v33
	s_nop 1
	v_subb_co_u32_e32 v31, vcc, v31, v33, vcc
	global_atomic_add_x2 v[26:27], v[30:31], off

; #define PG8_STAGE(bufoff, gbase, voff) do { const char* gb_ = (const char*)(gbase); asm volatile("" : "+s"(gb_)); _Pragma("unroll") for (int _i = 0; _i < 2; ++_i) { unsigned vo_ = (voff)[_i]; asm volatile("" : "+v"(vo_));        \
;         __builtin_amdgcn_global_load_lds((const unsigned*)(gb_ + vo_), (PG8_LAS unsigned*)(lds + (bufoff) + ldsw + _i * 8192), 16, 0, 0); } } while (0)
; #define PG8_LDA(dst, b, h) do { _Pragma("unroll") for (int m = 0; m < 4; ++m) _Pragma("unroll") for (int k = 0; k < 2; ++k) dst[m][k] = *(const PG8_LAS bf16x8*)(lds + PG8_SA(b, h) + aoff + m * 2048 + k * 1024); } while (0)
; #define PG8_LDB(dst, b, h) do { _Pragma("unroll") for (int n = 0; n < 2; ++n) _Pragma("unroll") for (int k = 0; k < 2; ++k) dst[n][k] = *(const PG8_LAS bf16x8*)(lds + PG8_SB(b, h) + boff + n * 2048 + k * 1024); } while (0)
; #define PG8_MMA(ai, bj, At, Bt) do { __builtin_amdgcn_s_setprio(1); _Pragma("unroll") for (int m = 0; m < 4; ++m) _Pragma("unroll") for (int n = 0; n < 2; ++n) _Pragma("unroll") for (int k = 0; k < 2; ++k) \
;         acc[ai][bj][m][n] = __builtin_amdgcn_mfma_f32_16x16x32_bf16(Bt[n][k], At[m][k], acc[ai][bj][m][n], 0, 0, 0); __builtin_amdgcn_s_setprio(0); } while (0)
; #define PG8_WAIT_V(n) asm volatile("s_waitcnt vmcnt(" #n ")" ::: "memory")
; template <class Epi, class Sched, bool ALIGN_EPI = false, bool SP2 = false>
; __device__ __forceinline__ void gemm_phase(PG8_LAS unsigned char* lds, const Gemm g, const Sched& S, const Epi& E) {
;     ...
;             const bool last = (t == nt - 2);
;             const char* a1 = cA + (size_t)(t + 1) * kstep;
;             const char* a2 = last ? nA : cA + (size_t)(t + 2) * kstep; const char* b2 = last ? nB : cB + (size_t)(t + 2) * kstep;
;             const char* a3 = a2 + kstep; const char* b3 = b2 + kstep;
;             if (last && has_next) S.a_ready(nxt);
;             if constexpr (SP2) {
;             PG8_LDB(B0, 0, 0); PG8_LDB(B1, 0, 1); PG8_SCHED; PG8_LDA(At, 0, 0); PG8_STAGE(PG8_SA(1, 1), a1 + hstep, voffA);
;             PG8_WAIT_V(8); PG8_WAIT_L(0); PG8_BAR; PG8_MMA(0, 0, At, B0); PG8_MMA(0, 1, At, B1); PG8_BAR; PG8_SCHED;
;             PG8_LDA(At, 0, 1); PG8_STAGE(PG8_SB(0, 0), b2, voffB); PG8_STAGE(PG8_SB(0, 1), b2 + hstep, voffB); PG8_STAGE(PG8_SA(0, 0), a2, voffA);
;             PG8_WAIT_V(8); PG8_WAIT_L(0); PG8_BAR; PG8_MMA(1, 0, At, B0); PG8_MMA(1, 1, At, B1); PG8_BAR; PG8_SCHED;
.LBB0_634:
	s_add_u32 s16, s14, 0x100
	s_addc_u32 s17, s15, 0
	s_cmp_eq_u32 s53, 28
	s_cselect_b32 s22, s49, s16
	s_cselect_b32 s23, s7, s17
	s_cselect_b32 s20, s50, s51
	s_cselect_b32 s21, s5, s52
	s_add_u32 s18, s22, 0x80
	s_addc_u32 s19, s23, 0
	s_add_i32 s54, 0, 0x10000
	s_add_i32 s55, 0, 0x14000
	ds_read_b128 v[82:85], v244
	ds_read_b128 v[86:89], v244 offset:1024
	ds_read_b128 v[90:93], v244 offset:2048
	ds_read_b128 v[94:97], v244 offset:3072
	ds_read_b128 v[146:149], v244 offset:16384
	ds_read_b128 v[150:153], v244 offset:17408
	ds_read_b128 v[154:157], v244 offset:18432
	ds_read_b128 v[158:161], v244 offset:19456
	s_add_u32 s14, s14, 0x80080
	s_addc_u32 s15, s15, 0
	ds_read_b128 v[178:181], v188
	ds_read_b128 v[190:193], v188 offset:1024
	ds_read_b128 v[194:197], v188 offset:2048
	ds_read_b128 v[198:201], v188 offset:3072
	ds_read_b128 v[202:205], v188 offset:4096
	ds_read_b128 v[206:209], v188 offset:5120
	ds_read_b128 v[210:213], v188 offset:6144
	ds_read_b128 v[220:223], v188 offset:7168
	s_add_i32 m0, s27, 0xc000
	s_nop 0
	global_load_lds_dwordx4 v1, s[14:15]
	s_add_i32 m0, s27, 0xe000
	s_nop 0
	global_load_lds_dwordx4 v164, s[14:15]
	s_waitcnt vmcnt(8)
	s_waitcnt lgkmcnt(0)
	s_barrier
	s_setprio 1
	s_waitcnt lgkmcnt(0)
	v_mfma_f32_16x16x32_bf16 v[142:145], v[82:85], v[178:181], v[142:145]
	v_mfma_f32_16x16x32_bf16 v[142:145], v[86:89], v[190:193], v[142:145]
	v_mfma_f32_16x16x32_bf16 v[126:129], v[82:85], v[194:197], v[126:129]
	v_mfma_f32_16x16x32_bf16 v[126:129], v[86:89], v[198:201], v[126:129]
	v_mfma_f32_16x16x32_bf16 v[110:113], v[82:85], v[202:205], v[110:113]
	v_mfma_f32_16x16x32_bf16 v[110:113], v[86:89], v[206:209], v[110:113]
	v_mfma_f32_16x16x32_bf16 v[78:81], v[82:85], v[210:213], v[78:81]
	v_mfma_f32_16x16x32_bf16 v[78:81], v[86:89], v[220:223], v[78:81]
	v_mfma_f32_16x16x32_bf16 v[138:141], v[90:93], v[178:181], v[138:141]
	v_mfma_f32_16x16x32_bf16 v[138:141], v[94:97], v[190:193], v[138:141]
	v_mfma_f32_16x16x32_bf16 v[122:125], v[90:93], v[194:197], v[122:125]
	v_mfma_f32_16x16x32_bf16 v[122:125], v[94:97], v[198:201], v[122:125]
	v_mfma_f32_16x16x32_bf16 v[106:109], v[90:93], v[202:205], v[106:109]
	v_mfma_f32_16x16x32_bf16 v[106:109], v[94:97], v[206:209], v[106:109]
	v_mfma_f32_16x16x32_bf16 v[74:77], v[90:93], v[210:213], v[74:77]
	v_mfma_f32_16x16x32_bf16 v[74:77], v[94:97], v[220:223], v[74:77]
	s_setprio 0
	s_setprio 1
	v_mfma_f32_16x16x32_bf16 v[134:137], v[146:149], v[178:181], v[134:137]
	v_mfma_f32_16x16x32_bf16 v[134:137], v[150:153], v[190:193], v[134:137]
	v_mfma_f32_16x16x32_bf16 v[118:121], v[146:149], v[194:197], v[118:121]
	v_mfma_f32_16x16x32_bf16 v[118:121], v[150:153], v[198:201], v[118:121]
	v_mfma_f32_16x16x32_bf16 v[102:105], v[146:149], v[202:205], v[102:105]
	v_mfma_f32_16x16x32_bf16 v[102:105], v[150:153], v[206:209], v[102:105]
	v_mfma_f32_16x16x32_bf16 v[70:73], v[146:149], v[210:213], v[70:73]
	v_mfma_f32_16x16x32_bf16 v[70:73], v[150:153], v[220:223], v[70:73]
	v_mfma_f32_16x16x32_bf16 v[130:133], v[154:157], v[178:181], v[130:133]
	v_mfma_f32_16x16x32_bf16 v[130:133], v[158:161], v[190:193], v[130:133]
	v_mfma_f32_16x16x32_bf16 v[114:117], v[154:157], v[194:197], v[114:117]
	v_mfma_f32_16x16x32_bf16 v[114:117], v[158:161], v[198:201], v[114:117]
	v_mfma_f32_16x16x32_bf16 v[98:101], v[154:157], v[202:205], v[98:101]
	v_mfma_f32_16x16x32_bf16 v[98:101], v[158:161], v[206:209], v[98:101]
	v_mfma_f32_16x16x32_bf16 v[66:69], v[154:157], v[210:213], v[66:69]
	v_mfma_f32_16x16x32_bf16 v[66:69], v[158:161], v[220:223], v[66:69]
	s_setprio 0
	s_barrier
	s_mov_b64 s[14:15], s[20:21]
	s_add_i32 s54, s54, s26
	ds_read_b128 v[178:181], v188 offset:16384
	ds_read_b128 v[190:193], v188 offset:17408
	ds_read_b128 v[194:197], v188 offset:18432
	ds_read_b128 v[198:201], v188 offset:19456
	ds_read_b128 v[202:205], v188 offset:20480
	ds_read_b128 v[206:209], v188 offset:21504
	ds_read_b128 v[210:213], v188 offset:22528
	ds_read_b128 v[220:223], v188 offset:23552
	s_mov_b32 m0, s54
	s_nop 0
	global_load_lds_dwordx4 v162, s[14:15]
	s_add_i32 m0, s54, 0x2000
	s_nop 0
	global_load_lds_dwordx4 v184, s[14:15]
	s_add_u32 s14, s20, 0x80000
	s_addc_u32 s15, s21, 0
	s_add_i32 s54, s55, s26
	s_mov_b32 m0, s54
	s_nop 0
	global_load_lds_dwordx4 v162, s[14:15]
	s_add_i32 m0, s54, 0x2000
	s_nop 0
	global_load_lds_dwordx4 v184, s[14:15]
	s_mov_b64 s[14:15], s[22:23]
	s_mov_b32 m0, s27
	s_nop 0
	global_load_lds_dwordx4 v1, s[14:15]
	s_mov_b32 m0, s28
	s_nop 0
	global_load_lds_dwordx4 v164, s[14:15]
	s_waitcnt vmcnt(8)
	s_waitcnt lgkmcnt(0)
	s_barrier
; #define PG8_STAGE(bufoff, gbase, voff) do { const char* gb_ = (const char*)(gbase); asm volatile("" : "+s"(gb_)); _Pragma("unroll") for (int _i = 0; _i < 2; ++_i) { unsigned vo_ = (voff)[_i]; asm volatile("" : "+v"(vo_));        \
;         __builtin_amdgcn_global_load_lds((const unsigned*)(gb_ + vo_), (PG8_LAS unsigned*)(lds + (bufoff) + ldsw + _i * 8192), 16, 0, 0); } } while (0)
; #define PG8_LDA(dst, b, h) do { _Pragma("unroll") for (int m = 0; m < 4; ++m) _Pragma("unroll") for (int k = 0; k < 2; ++k) dst[m][k] = *(const PG8_LAS bf16x8*)(lds + PG8_SA(b, h) + aoff + m * 2048 + k * 1024); } while (0)
; #define PG8_LDB(dst, b, h) do { _Pragma("unroll") for (int n = 0; n < 2; ++n) _Pragma("unroll") for (int k = 0; k < 2; ++k) dst[n][k] = *(const PG8_LAS bf16x8*)(lds + PG8_SB(b, h) + boff + n * 2048 + k * 1024); } while (0)
; #define PG8_MMA(ai, bj, At, Bt) do { __builtin_amdgcn_s_setprio(1); _Pragma("unroll") for (int m = 0; m < 4; ++m) _Pragma("unroll") for (int n = 0; n < 2; ++n) _Pragma("unroll") for (int k = 0; k < 2; ++k) \
;         acc[ai][bj][m][n] = __builtin_amdgcn_mfma_f32_16x16x32_bf16(Bt[n][k], At[m][k], acc[ai][bj][m][n], 0, 0, 0); __builtin_amdgcn_s_setprio(0); } while (0)
; #define PG8_WAIT_V(n) asm volatile("s_waitcnt vmcnt(" #n ")" ::: "memory")
; #define PG8_WAIT_L(n) asm volatile("s_waitcnt lgkmcnt(" #n ")" ::: "memory")
; #define PG8_BAR __builtin_amdgcn_s_barrier()
; #define PG8_SCHED __builtin_amdgcn_sched_barrier(0)
; template <class Epi, class Sched, bool ALIGN_EPI = false, bool SP2 = false>
; __device__ __forceinline__ void gemm_phase(PG8_LAS unsigned char* lds, const Gemm g, const Sched& S, const Epi& E) {
;     ...
;             PG8_WAIT_V(8); PG8_WAIT_L(0); PG8_BAR; PG8_MMA(0, 0, At, B0); PG8_MMA(0, 1, At, B1); PG8_BAR; PG8_SCHED;
;             PG8_LDA(At, 0, 1); PG8_STAGE(PG8_SB(0, 0), b2, voffB); PG8_STAGE(PG8_SB(0, 1), b2 + hstep, voffB); PG8_STAGE(PG8_SA(0, 0), a2, voffA);
;             PG8_WAIT_V(8); PG8_WAIT_L(0); PG8_BAR; PG8_MMA(1, 0, At, B0); PG8_MMA(1, 1, At, B1); PG8_BAR; PG8_SCHED;
;             PG8_LDB(B0, 1, 0); PG8_LDB(B1, 1, 1); PG8_SCHED; PG8_LDA(At, 1, 0); PG8_STAGE(PG8_SA(0, 1), a2 + hstep, voffA);
;             PG8_WAIT_V(8); PG8_WAIT_L(0); PG8_BAR; PG8_MMA(0, 0, At, B0); PG8_MMA(0, 1, At, B1); PG8_BAR; PG8_SCHED;
	s_setprio 1
	s_waitcnt lgkmcnt(0)
	v_mfma_f32_16x16x32_bf16 v[62:65], v[82:85], v[178:181], v[62:65]
	v_mfma_f32_16x16x32_bf16 v[62:65], v[86:89], v[190:193], v[62:65]
	v_mfma_f32_16x16x32_bf16 v[46:49], v[82:85], v[194:197], v[46:49]
	v_mfma_f32_16x16x32_bf16 v[46:49], v[86:89], v[198:201], v[46:49]
	v_mfma_f32_16x16x32_bf16 v[30:33], v[82:85], v[202:205], v[30:33]
	v_mfma_f32_16x16x32_bf16 v[30:33], v[86:89], v[206:209], v[30:33]
	v_mfma_f32_16x16x32_bf16 v[14:17], v[82:85], v[210:213], v[14:17]
	v_mfma_f32_16x16x32_bf16 v[14:17], v[86:89], v[220:223], v[14:17]
	v_mfma_f32_16x16x32_bf16 v[58:61], v[90:93], v[178:181], v[58:61]
	v_mfma_f32_16x16x32_bf16 v[58:61], v[94:97], v[190:193], v[58:61]
	v_mfma_f32_16x16x32_bf16 v[42:45], v[90:93], v[194:197], v[42:45]
	v_mfma_f32_16x16x32_bf16 v[42:45], v[94:97], v[198:201], v[42:45]
	v_mfma_f32_16x16x32_bf16 v[26:29], v[90:93], v[202:205], v[26:29]
	v_mfma_f32_16x16x32_bf16 v[26:29], v[94:97], v[206:209], v[26:29]
	v_mfma_f32_16x16x32_bf16 v[10:13], v[90:93], v[210:213], v[10:13]
	v_mfma_f32_16x16x32_bf16 v[10:13], v[94:97], v[220:223], v[10:13]
	s_setprio 0
	s_setprio 1
	v_mfma_f32_16x16x32_bf16 v[54:57], v[146:149], v[178:181], v[54:57]
	v_mfma_f32_16x16x32_bf16 v[54:57], v[150:153], v[190:193], v[54:57]
	v_mfma_f32_16x16x32_bf16 v[38:41], v[146:149], v[194:197], v[38:41]
	v_mfma_f32_16x16x32_bf16 v[38:41], v[150:153], v[198:201], v[38:41]
	v_mfma_f32_16x16x32_bf16 v[22:25], v[146:149], v[202:205], v[22:25]
	v_mfma_f32_16x16x32_bf16 v[22:25], v[150:153], v[206:209], v[22:25]
	v_mfma_f32_16x16x32_bf16 v[6:9], v[146:149], v[210:213], v[6:9]
	v_mfma_f32_16x16x32_bf16 v[6:9], v[150:153], v[220:223], v[6:9]
	v_mfma_f32_16x16x32_bf16 v[50:53], v[154:157], v[178:181], v[50:53]
	v_mfma_f32_16x16x32_bf16 v[50:53], v[158:161], v[190:193], v[50:53]
	v_mfma_f32_16x16x32_bf16 v[34:37], v[154:157], v[194:197], v[34:37]
	v_mfma_f32_16x16x32_bf16 v[34:37], v[158:161], v[198:201], v[34:37]
	v_mfma_f32_16x16x32_bf16 v[18:21], v[154:157], v[202:205], v[18:21]
	v_mfma_f32_16x16x32_bf16 v[18:21], v[158:161], v[206:209], v[18:21]
	v_mfma_f32_16x16x32_bf16 v[2:5], v[154:157], v[210:213], v[2:5]
	v_mfma_f32_16x16x32_bf16 v[2:5], v[158:161], v[220:223], v[2:5]
	s_setprio 0
	s_barrier
	s_add_i32 s54, 0, 0x18000
	s_add_i32 s55, 0, 0x1c000
	ds_read_b128 v[82:85], v244 offset:32768
	ds_read_b128 v[86:89], v244 offset:33792
	ds_read_b128 v[90:93], v244 offset:34816
	ds_read_b128 v[94:97], v244 offset:35840
	ds_read_b128 v[146:149], v244 offset:49152
	ds_read_b128 v[150:153], v244 offset:50176
	ds_read_b128 v[154:157], v244 offset:51200
	ds_read_b128 v[158:161], v244 offset:52224
	s_add_u32 s14, s22, 0x80000
	s_addc_u32 s15, s23, 0
	s_mov_b32 m0, s29
	ds_read_b128 v[178:181], v188 offset:32768
	ds_read_b128 v[190:193], v188 offset:33792
	ds_read_b128 v[194:197], v188 offset:34816
	ds_read_b128 v[198:201], v188 offset:35840
	ds_read_b128 v[202:205], v188 offset:36864
	ds_read_b128 v[206:209], v188 offset:37888
	ds_read_b128 v[210:213], v188 offset:38912
	ds_read_b128 v[220:223], v188 offset:39936
	s_nop 0
	global_load_lds_dwordx4 v1, s[14:15]
	s_mov_b32 m0, s33
	s_nop 0
	global_load_lds_dwordx4 v164, s[14:15]
	s_waitcnt vmcnt(8)
	s_waitcnt lgkmcnt(0)
	s_barrier
	s_setprio 1
	s_waitcnt lgkmcnt(0)
	v_mfma_f32_16x16x32_bf16 v[142:145], v[82:85], v[178:181], v[142:145]
	v_mfma_f32_16x16x32_bf16 v[142:145], v[86:89], v[190:193], v[142:145]
	v_mfma_f32_16x16x32_bf16 v[126:129], v[82:85], v[194:197], v[126:129]
	v_mfma_f32_16x16x32_bf16 v[126:129], v[86:89], v[198:201], v[126:129]
	v_mfma_f32_16x16x32_bf16 v[110:113], v[82:85], v[202:205], v[110:113]
	v_mfma_f32_16x16x32_bf16 v[110:113], v[86:89], v[206:209], v[110:113]
	v_mfma_f32_16x16x32_bf16 v[78:81], v[82:85], v[210:213], v[78:81]
	v_mfma_f32_16x16x32_bf16 v[78:81], v[86:89], v[220:223], v[78:81]
	v_mfma_f32_16x16x32_bf16 v[138:141], v[90:93], v[178:181], v[138:141]
	v_mfma_f32_16x16x32_bf16 v[138:141], v[94:97], v[190:193], v[138:141]
	v_mfma_f32_16x16x32_bf16 v[122:125], v[90:93], v[194:197], v[122:125]
	v_mfma_f32_16x16x32_bf16 v[122:125], v[94:97], v[198:201], v[122:125]
	v_mfma_f32_16x16x32_bf16 v[106:109], v[90:93], v[202:205], v[106:109]
	v_mfma_f32_16x16x32_bf16 v[106:109], v[94:97], v[206:209], v[106:109]
	v_mfma_f32_16x16x32_bf16 v[74:77], v[90:93], v[210:213], v[74:77]
	v_mfma_f32_16x16x32_bf16 v[74:77], v[94:97], v[220:223], v[74:77]
	s_setprio 0
	s_setprio 1
	v_mfma_f32_16x16x32_bf16 v[134:137], v[146:149], v[178:181], v[134:137]
	v_mfma_f32_16x16x32_bf16 v[134:137], v[150:153], v[190:193], v[134:137]
	v_mfma_f32_16x16x32_bf16 v[118:121], v[146:149], v[194:197], v[118:121]
	v_mfma_f32_16x16x32_bf16 v[118:121], v[150:153], v[198:201], v[118:121]
	v_mfma_f32_16x16x32_bf16 v[102:105], v[146:149], v[202:205], v[102:105]
	v_mfma_f32_16x16x32_bf16 v[102:105], v[150:153], v[206:209], v[102:105]
	v_mfma_f32_16x16x32_bf16 v[70:73], v[146:149], v[210:213], v[70:73]
	v_mfma_f32_16x16x32_bf16 v[70:73], v[150:153], v[220:223], v[70:73]
	v_mfma_f32_16x16x32_bf16 v[130:133], v[154:157], v[178:181], v[130:133]
	v_mfma_f32_16x16x32_bf16 v[130:133], v[158:161], v[190:193], v[130:133]
	v_mfma_f32_16x16x32_bf16 v[114:117], v[154:157], v[194:197], v[114:117]
	v_mfma_f32_16x16x32_bf16 v[114:117], v[158:161], v[198:201], v[114:117]
	v_mfma_f32_16x16x32_bf16 v[98:101], v[154:157], v[202:205], v[98:101]
	v_mfma_f32_16x16x32_bf16 v[98:101], v[158:161], v[206:209], v[98:101]
	v_mfma_f32_16x16x32_bf16 v[66:69], v[154:157], v[210:213], v[66:69]
	v_mfma_f32_16x16x32_bf16 v[66:69], v[158:161], v[220:223], v[66:69]
	s_setprio 0
	s_barrier
; #define PG8_LDA(dst, b, h) do { _Pragma("unroll") for (int m = 0; m < 4; ++m) _Pragma("unroll") for (int k = 0; k < 2; ++k) dst[m][k] = *(const PG8_LAS bf16x8*)(lds + PG8_SA(b, h) + aoff + m * 2048 + k * 1024); } while (0)
; #define PG8_WAIT_V(n) asm volatile("s_waitcnt vmcnt(" #n ")" ::: "memory")
; template <class Epi, class Sched, bool ALIGN_EPI = false, bool SP2 = false>
; __device__ __forceinline__ void gemm_phase(PG8_LAS unsigned char* lds, const Gemm g, const Sched& S, const Epi& E) {
;     ...
;             PG8_LDB(B0, 1, 0); PG8_LDB(B1, 1, 1); PG8_SCHED; PG8_LDA(At, 1, 0); PG8_STAGE(PG8_SA(0, 1), a2 + hstep, voffA);
;             PG8_WAIT_V(8); PG8_WAIT_L(0); PG8_BAR; PG8_MMA(0, 0, At, B0); PG8_MMA(0, 1, At, B1); PG8_BAR; PG8_SCHED;
;             PG8_LDA(At, 1, 1); PG8_STAGE(PG8_SB(1, 0), b3, voffB); PG8_STAGE(PG8_SB(1, 1), b3 + hstep, voffB); PG8_STAGE(PG8_SA(1, 0), a3, voffA);
;             PG8_WAIT_V(8); PG8_WAIT_L(0); PG8_BAR; PG8_MMA(1, 0, At, B0); PG8_MMA(1, 1, At, B1); PG8_BAR; PG8_SCHED;
;             } else {
;             PG8_LDB(B0, 0, 0); PG8_SCHED; PG8_LDA(At, 0, 0); PG8_STAGE(PG8_SA(1, 1), a1 + hstep, voffA);
;             PG8_WAIT_L(8); PG8_BAR; PG8_WAIT_L(0); PG8_MMA(0, 0, At, B0); PG8_BAR; PG8_SCHED;
;             PG8_LDB(B1, 0, 1); PG8_STAGE(PG8_SB(0, 0), b2, voffB);
;             PG8_BAR; PG8_WAIT_L(0); PG8_MMA(0, 1, At, B1); PG8_BAR;
;             PG8_LDA(At, 0, 1); PG8_STAGE(PG8_SA(0, 0), a2, voffA);
;             PG8_BAR; PG8_WAIT_L(0); PG8_MMA(1, 0, At, B0); PG8_BAR; PG8_SCHED;
;             PG8_STAGE(PG8_SB(0, 1), b2 + hstep, voffB);
;             PG8_WAIT_V(6); PG8_BAR; PG8_MMA(1, 1, At, B1); PG8_BAR;
;             PG8_LDB(B0, 1, 0); PG8_SCHED; PG8_LDA(At, 1, 0); PG8_STAGE(PG8_SA(0, 1), a2 + hstep, voffA);
;             PG8_WAIT_L(8); PG8_BAR; PG8_WAIT_L(0); PG8_MMA(0, 0, At, B0); PG8_BAR; PG8_SCHED;
;             PG8_LDB(B1, 1, 1); PG8_STAGE(PG8_SB(1, 0), b3, voffB);
;             PG8_BAR; PG8_WAIT_L(0); PG8_MMA(0, 1, At, B1); PG8_BAR;
;             PG8_LDA(At, 1, 1); PG8_STAGE(PG8_SA(1, 0), a3, voffA);
;             PG8_BAR; PG8_WAIT_L(0); PG8_MMA(1, 0, At, B0); PG8_BAR; PG8_SCHED;
;             PG8_STAGE(PG8_SB(1, 1), b3 + hstep, voffB);
;             PG8_WAIT_V(6); PG8_BAR; PG8_MMA(1, 1, At, B1); PG8_BAR;
;             }
;         }
;         if constexpr (ALIGN_EPI) { if (wr == 0) PG8_BAR; }
	s_add_u32 s14, s20, 0x80
	s_addc_u32 s15, s21, 0
	s_add_i32 s22, s54, s26
	ds_read_b128 v[178:181], v188 offset:49152
	ds_read_b128 v[190:193], v188 offset:50176
	ds_read_b128 v[194:197], v188 offset:51200
	ds_read_b128 v[198:201], v188 offset:52224
	ds_read_b128 v[202:205], v188 offset:53248
	ds_read_b128 v[206:209], v188 offset:54272
	ds_read_b128 v[210:213], v188 offset:55296
	ds_read_b128 v[220:223], v188 offset:56320
	s_mov_b32 m0, s22
	s_nop 0
	global_load_lds_dwordx4 v162, s[14:15]
	s_add_i32 m0, s22, 0x2000
	s_nop 0
	global_load_lds_dwordx4 v184, s[14:15]
	s_add_u32 s14, s20, 0x80080
	s_addc_u32 s15, s21, 0
	s_add_i32 s20, s55, s26
	s_mov_b32 m0, s20
	s_nop 0
	global_load_lds_dwordx4 v162, s[14:15]
	s_add_i32 m0, s20, 0x2000
	s_nop 0
	global_load_lds_dwordx4 v184, s[14:15]
	s_mov_b32 m0, s38
	s_nop 0
	global_load_lds_dwordx4 v1, s[18:19]
	s_mov_b32 m0, s39
	s_nop 0
	global_load_lds_dwordx4 v164, s[18:19]
	s_waitcnt vmcnt(8)
	s_waitcnt lgkmcnt(0)
	s_barrier
	s_setprio 1
	s_waitcnt lgkmcnt(0)
	v_mfma_f32_16x16x32_bf16 v[62:65], v[82:85], v[178:181], v[62:65]
	v_mfma_f32_16x16x32_bf16 v[62:65], v[86:89], v[190:193], v[62:65]
	v_mfma_f32_16x16x32_bf16 v[46:49], v[82:85], v[194:197], v[46:49]
	v_mfma_f32_16x16x32_bf16 v[46:49], v[86:89], v[198:201], v[46:49]
	v_mfma_f32_16x16x32_bf16 v[30:33], v[82:85], v[202:205], v[30:33]
	v_mfma_f32_16x16x32_bf16 v[30:33], v[86:89], v[206:209], v[30:33]
	v_mfma_f32_16x16x32_bf16 v[14:17], v[82:85], v[210:213], v[14:17]
	v_mfma_f32_16x16x32_bf16 v[14:17], v[86:89], v[220:223], v[14:17]
	v_mfma_f32_16x16x32_bf16 v[58:61], v[90:93], v[178:181], v[58:61]
	v_mfma_f32_16x16x32_bf16 v[58:61], v[94:97], v[190:193], v[58:61]
	v_mfma_f32_16x16x32_bf16 v[42:45], v[90:93], v[194:197], v[42:45]
	v_mfma_f32_16x16x32_bf16 v[42:45], v[94:97], v[198:201], v[42:45]
	v_mfma_f32_16x16x32_bf16 v[26:29], v[90:93], v[202:205], v[26:29]
	v_mfma_f32_16x16x32_bf16 v[26:29], v[94:97], v[206:209], v[26:29]
	v_mfma_f32_16x16x32_bf16 v[10:13], v[90:93], v[210:213], v[10:13]
	v_mfma_f32_16x16x32_bf16 v[10:13], v[94:97], v[220:223], v[10:13]
	s_setprio 0
	s_setprio 1
	v_mfma_f32_16x16x32_bf16 v[54:57], v[146:149], v[178:181], v[54:57]
	v_mfma_f32_16x16x32_bf16 v[54:57], v[150:153], v[190:193], v[54:57]
	v_mfma_f32_16x16x32_bf16 v[38:41], v[146:149], v[194:197], v[38:41]
	v_mfma_f32_16x16x32_bf16 v[38:41], v[150:153], v[198:201], v[38:41]
	v_mfma_f32_16x16x32_bf16 v[22:25], v[146:149], v[202:205], v[22:25]
	v_mfma_f32_16x16x32_bf16 v[22:25], v[150:153], v[206:209], v[22:25]
	v_mfma_f32_16x16x32_bf16 v[6:9], v[146:149], v[210:213], v[6:9]
	v_mfma_f32_16x16x32_bf16 v[6:9], v[150:153], v[220:223], v[6:9]
	v_mfma_f32_16x16x32_bf16 v[50:53], v[154:157], v[178:181], v[50:53]
	v_mfma_f32_16x16x32_bf16 v[50:53], v[158:161], v[190:193], v[50:53]
	v_mfma_f32_16x16x32_bf16 v[34:37], v[154:157], v[194:197], v[34:37]
	v_mfma_f32_16x16x32_bf16 v[34:37], v[158:161], v[198:201], v[34:37]
	v_mfma_f32_16x16x32_bf16 v[18:21], v[154:157], v[202:205], v[18:21]
	v_mfma_f32_16x16x32_bf16 v[18:21], v[158:161], v[206:209], v[18:21]
	v_mfma_f32_16x16x32_bf16 v[2:5], v[154:157], v[210:213], v[2:5]
	v_mfma_f32_16x16x32_bf16 v[2:5], v[158:161], v[220:223], v[2:5]
	s_setprio 0
	s_barrier
	s_add_i32 s53, s53, 2
	s_add_u32 s51, s51, 0x100
	s_addc_u32 s52, s52, 0
	s_cmp_gt_u32 s53, 29
	s_mov_b64 s[14:15], s[16:17]
	s_cbranch_scc0 .LBB0_634
	s_and_b64 vcc, exec, s[2:3]
	s_cbranch_vccz .LBB0_637
	s_barrier

; #define PG8_STAGE(bufoff, gbase, voff) do { const char* gb_ = (const char*)(gbase); asm volatile("" : "+s"(gb_)); _Pragma("unroll") for (int _i = 0; _i < 2; ++_i) { unsigned vo_ = (voff)[_i]; asm volatile("" : "+v"(vo_));        \
;         __builtin_amdgcn_global_load_lds((const unsigned*)(gb_ + vo_), (PG8_LAS unsigned*)(lds + (bufoff) + ldsw + _i * 8192), 16, 0, 0); } } while (0)
; #define PG8_LDA(dst, b, h) do { _Pragma("unroll") for (int m = 0; m < 4; ++m) _Pragma("unroll") for (int k = 0; k < 2; ++k) dst[m][k] = *(const PG8_LAS bf16x8*)(lds + PG8_SA(b, h) + aoff + m * 2048 + k * 1024); } while (0)
; #define PG8_LDB(dst, b, h) do { _Pragma("unroll") for (int n = 0; n < 2; ++n) _Pragma("unroll") for (int k = 0; k < 2; ++k) dst[n][k] = *(const PG8_LAS bf16x8*)(lds + PG8_SB(b, h) + boff + n * 2048 + k * 1024); } while (0)
; #define PG8_MMA(ai, bj, At, Bt) do { __builtin_amdgcn_s_setprio(1); _Pragma("unroll") for (int m = 0; m < 4; ++m) _Pragma("unroll") for (int n = 0; n < 2; ++n) _Pragma("unroll") for (int k = 0; k < 2; ++k) \
;         acc[ai][bj][m][n] = __builtin_amdgcn_mfma_f32_16x16x32_bf16(Bt[n][k], At[m][k], acc[ai][bj][m][n], 0, 0, 0); __builtin_amdgcn_s_setprio(0); } while (0)
; #define PG8_WAIT_V(n) asm volatile("s_waitcnt vmcnt(" #n ")" ::: "memory")
; template <class Epi, class Sched, bool ALIGN_EPI = false, bool SP2 = false>
; __device__ __forceinline__ void gemm_phase(PG8_LAS unsigned char* lds, const Gemm g, const Sched& S, const Epi& E) {
;     ...
;             const bool last = (t == nt - 2);
;             const char* a1 = cA + (size_t)(t + 1) * kstep;
;             const char* a2 = last ? nA : cA + (size_t)(t + 2) * kstep; const char* b2 = last ? nB : cB + (size_t)(t + 2) * kstep;
;             const char* a3 = a2 + kstep; const char* b3 = b2 + kstep;
;             if (last && has_next) S.a_ready(nxt);
;             if constexpr (SP2) {
;             PG8_LDB(B0, 0, 0); PG8_LDB(B1, 0, 1); PG8_SCHED; PG8_LDA(At, 0, 0); PG8_STAGE(PG8_SA(1, 1), a1 + hstep, voffA);
;             PG8_WAIT_V(8); PG8_WAIT_L(0); PG8_BAR; PG8_MMA(0, 0, At, B0); PG8_MMA(0, 1, At, B1); PG8_BAR; PG8_SCHED;
;             PG8_LDA(At, 0, 1); PG8_STAGE(PG8_SB(0, 0), b2, voffB); PG8_STAGE(PG8_SB(0, 1), b2 + hstep, voffB); PG8_STAGE(PG8_SA(0, 0), a2, voffA);
;             PG8_WAIT_V(8); PG8_WAIT_L(0); PG8_BAR; PG8_MMA(1, 0, At, B0); PG8_MMA(1, 1, At, B1); PG8_BAR; PG8_SCHED;
.LBB0_707:
	s_add_u32 s2, s4, 0x100
	s_addc_u32 s3, s5, 0
	s_cmpk_eq_i32 s35, 0x54
	s_cselect_b32 s10, s52, s2
	s_cselect_b32 s11, s53, s3
	s_cselect_b32 s8, s42, s31
	s_cselect_b32 s9, s43, s34
	s_add_u32 s6, s10, 0x80
	s_addc_u32 s7, s11, 0
	s_add_i32 s38, 0, 0x10000
	s_add_i32 s39, 0, 0x14000
	ds_read_b128 v[34:37], v244
	ds_read_b128 v[38:41], v244 offset:1024
	ds_read_b128 v[98:101], v244 offset:2048
	ds_read_b128 v[102:105], v244 offset:3072
	ds_read_b128 v[146:149], v244 offset:16384
	ds_read_b128 v[150:153], v244 offset:17408
	ds_read_b128 v[154:157], v244 offset:18432
	ds_read_b128 v[158:161], v244 offset:19456
	s_add_u32 s4, s4, 0x160080
	s_addc_u32 s5, s5, 0
	ds_read_b128 v[178:181], v194
	ds_read_b128 v[182:185], v194 offset:1024
	ds_read_b128 v[186:189], v194 offset:2048
	ds_read_b128 v[196:199], v194 offset:3072
	ds_read_b128 v[200:203], v194 offset:4096
	ds_read_b128 v[204:207], v194 offset:5120
	ds_read_b128 v[208:211], v194 offset:6144
	ds_read_b128 v[212:215], v194 offset:7168
	s_add_i32 m0, s16, 0xc000
	s_nop 0
	global_load_lds_dwordx4 v1, s[4:5]
	s_add_i32 m0, s16, 0xe000
	s_nop 0
	global_load_lds_dwordx4 v164, s[4:5]
	s_waitcnt vmcnt(8)
	s_waitcnt lgkmcnt(0)
	s_barrier
	s_setprio 1
	s_waitcnt lgkmcnt(0)
	v_mfma_f32_16x16x32_bf16 v[142:145], v[34:37], v[178:181], v[142:145]
	v_mfma_f32_16x16x32_bf16 v[142:145], v[38:41], v[182:185], v[142:145]
	v_mfma_f32_16x16x32_bf16 v[134:137], v[34:37], v[186:189], v[134:137]
	v_mfma_f32_16x16x32_bf16 v[134:137], v[38:41], v[196:199], v[134:137]
	v_mfma_f32_16x16x32_bf16 v[126:129], v[34:37], v[200:203], v[126:129]
	v_mfma_f32_16x16x32_bf16 v[126:129], v[38:41], v[204:207], v[126:129]
	v_mfma_f32_16x16x32_bf16 v[118:121], v[34:37], v[208:211], v[118:121]
	v_mfma_f32_16x16x32_bf16 v[118:121], v[38:41], v[212:215], v[118:121]
	v_mfma_f32_16x16x32_bf16 v[138:141], v[98:101], v[178:181], v[138:141]
	v_mfma_f32_16x16x32_bf16 v[138:141], v[102:105], v[182:185], v[138:141]
	v_mfma_f32_16x16x32_bf16 v[130:133], v[98:101], v[186:189], v[130:133]
	v_mfma_f32_16x16x32_bf16 v[130:133], v[102:105], v[196:199], v[130:133]
	v_mfma_f32_16x16x32_bf16 v[122:125], v[98:101], v[200:203], v[122:125]
	v_mfma_f32_16x16x32_bf16 v[122:125], v[102:105], v[204:207], v[122:125]
	v_mfma_f32_16x16x32_bf16 v[114:117], v[98:101], v[208:211], v[114:117]
	v_mfma_f32_16x16x32_bf16 v[114:117], v[102:105], v[212:215], v[114:117]
	s_setprio 0
	s_setprio 1
	v_mfma_f32_16x16x32_bf16 v[70:73], v[146:149], v[178:181], v[70:73]
	v_mfma_f32_16x16x32_bf16 v[70:73], v[150:153], v[182:185], v[70:73]
	v_mfma_f32_16x16x32_bf16 v[62:65], v[146:149], v[186:189], v[62:65]
	v_mfma_f32_16x16x32_bf16 v[62:65], v[150:153], v[196:199], v[62:65]
	v_mfma_f32_16x16x32_bf16 v[54:57], v[146:149], v[200:203], v[54:57]
	v_mfma_f32_16x16x32_bf16 v[54:57], v[150:153], v[204:207], v[54:57]
	v_mfma_f32_16x16x32_bf16 v[46:49], v[146:149], v[208:211], v[46:49]
	v_mfma_f32_16x16x32_bf16 v[46:49], v[150:153], v[212:215], v[46:49]
	v_mfma_f32_16x16x32_bf16 v[66:69], v[154:157], v[178:181], v[66:69]
	v_mfma_f32_16x16x32_bf16 v[66:69], v[158:161], v[182:185], v[66:69]
	v_mfma_f32_16x16x32_bf16 v[58:61], v[154:157], v[186:189], v[58:61]
	v_mfma_f32_16x16x32_bf16 v[58:61], v[158:161], v[196:199], v[58:61]
	v_mfma_f32_16x16x32_bf16 v[50:53], v[154:157], v[200:203], v[50:53]
	v_mfma_f32_16x16x32_bf16 v[50:53], v[158:161], v[204:207], v[50:53]
	v_mfma_f32_16x16x32_bf16 v[42:45], v[154:157], v[208:211], v[42:45]
	v_mfma_f32_16x16x32_bf16 v[42:45], v[158:161], v[212:215], v[42:45]
	s_setprio 0
	s_barrier
	s_mov_b64 s[4:5], s[8:9]
	s_add_i32 s38, s38, s15
	ds_read_b128 v[178:181], v194 offset:16384
	ds_read_b128 v[182:185], v194 offset:17408
	ds_read_b128 v[186:189], v194 offset:18432
	ds_read_b128 v[196:199], v194 offset:19456
	ds_read_b128 v[200:203], v194 offset:20480
	ds_read_b128 v[204:207], v194 offset:21504
	ds_read_b128 v[208:211], v194 offset:22528
	ds_read_b128 v[212:215], v194 offset:23552
	s_mov_b32 m0, s38
	s_nop 0
	global_load_lds_dwordx4 v162, s[4:5]
	s_add_i32 m0, s38, 0x2000
	s_nop 0
	global_load_lds_dwordx4 v190, s[4:5]
	s_add_u32 s4, s8, 0x160000
	s_addc_u32 s5, s9, 0
	s_add_i32 s38, s39, s15
	s_mov_b32 m0, s38
	s_nop 0
	global_load_lds_dwordx4 v162, s[4:5]
	s_add_i32 m0, s38, 0x2000
	s_nop 0
	global_load_lds_dwordx4 v190, s[4:5]
	s_mov_b64 s[4:5], s[10:11]
	s_mov_b32 m0, s16
	s_nop 0
	global_load_lds_dwordx4 v1, s[4:5]
	s_mov_b32 m0, s17
	s_nop 0
	global_load_lds_dwordx4 v164, s[4:5]
	s_waitcnt vmcnt(8)
	s_waitcnt lgkmcnt(0)
	s_barrier
; #define PG8_STAGE(bufoff, gbase, voff) do { const char* gb_ = (const char*)(gbase); asm volatile("" : "+s"(gb_)); _Pragma("unroll") for (int _i = 0; _i < 2; ++_i) { unsigned vo_ = (voff)[_i]; asm volatile("" : "+v"(vo_));        \
;         __builtin_amdgcn_global_load_lds((const unsigned*)(gb_ + vo_), (PG8_LAS unsigned*)(lds + (bufoff) + ldsw + _i * 8192), 16, 0, 0); } } while (0)
; #define PG8_LDA(dst, b, h) do { _Pragma("unroll") for (int m = 0; m < 4; ++m) _Pragma("unroll") for (int k = 0; k < 2; ++k) dst[m][k] = *(const PG8_LAS bf16x8*)(lds + PG8_SA(b, h) + aoff + m * 2048 + k * 1024); } while (0)
; #define PG8_LDB(dst, b, h) do { _Pragma("unroll") for (int n = 0; n < 2; ++n) _Pragma("unroll") for (int k = 0; k < 2; ++k) dst[n][k] = *(const PG8_LAS bf16x8*)(lds + PG8_SB(b, h) + boff + n * 2048 + k * 1024); } while (0)
; #define PG8_MMA(ai, bj, At, Bt) do { __builtin_amdgcn_s_setprio(1); _Pragma("unroll") for (int m = 0; m < 4; ++m) _Pragma("unroll") for (int n = 0; n < 2; ++n) _Pragma("unroll") for (int k = 0; k < 2; ++k) \
;         acc[ai][bj][m][n] = __builtin_amdgcn_mfma_f32_16x16x32_bf16(Bt[n][k], At[m][k], acc[ai][bj][m][n], 0, 0, 0); __builtin_amdgcn_s_setprio(0); } while (0)
; #define PG8_WAIT_V(n) asm volatile("s_waitcnt vmcnt(" #n ")" ::: "memory")
; #define PG8_WAIT_L(n) asm volatile("s_waitcnt lgkmcnt(" #n ")" ::: "memory")
; #define PG8_BAR __builtin_amdgcn_s_barrier()
; #define PG8_SCHED __builtin_amdgcn_sched_barrier(0)
; template <class Epi, class Sched, bool ALIGN_EPI = false, bool SP2 = false>
; __device__ __forceinline__ void gemm_phase(PG8_LAS unsigned char* lds, const Gemm g, const Sched& S, const Epi& E) {
;     ...
;             PG8_WAIT_V(8); PG8_WAIT_L(0); PG8_BAR; PG8_MMA(0, 0, At, B0); PG8_MMA(0, 1, At, B1); PG8_BAR; PG8_SCHED;
;             PG8_LDA(At, 0, 1); PG8_STAGE(PG8_SB(0, 0), b2, voffB); PG8_STAGE(PG8_SB(0, 1), b2 + hstep, voffB); PG8_STAGE(PG8_SA(0, 0), a2, voffA);
;             PG8_WAIT_V(8); PG8_WAIT_L(0); PG8_BAR; PG8_MMA(1, 0, At, B0); PG8_MMA(1, 1, At, B1); PG8_BAR; PG8_SCHED;
;             PG8_LDB(B0, 1, 0); PG8_LDB(B1, 1, 1); PG8_SCHED; PG8_LDA(At, 1, 0); PG8_STAGE(PG8_SA(0, 1), a2 + hstep, voffA);
;             PG8_WAIT_V(8); PG8_WAIT_L(0); PG8_BAR; PG8_MMA(0, 0, At, B0); PG8_MMA(0, 1, At, B1); PG8_BAR; PG8_SCHED;
	s_setprio 1
	s_waitcnt lgkmcnt(0)
	v_mfma_f32_16x16x32_bf16 v[110:113], v[34:37], v[178:181], v[110:113]
	v_mfma_f32_16x16x32_bf16 v[110:113], v[38:41], v[182:185], v[110:113]
	v_mfma_f32_16x16x32_bf16 v[94:97], v[34:37], v[186:189], v[94:97]
	v_mfma_f32_16x16x32_bf16 v[94:97], v[38:41], v[196:199], v[94:97]
	v_mfma_f32_16x16x32_bf16 v[86:89], v[34:37], v[200:203], v[86:89]
	v_mfma_f32_16x16x32_bf16 v[86:89], v[38:41], v[204:207], v[86:89]
	v_mfma_f32_16x16x32_bf16 v[34:37], v[34:37], v[208:211], v[78:81]
	v_mfma_f32_16x16x32_bf16 v[34:37], v[38:41], v[212:215], v[34:37]
	v_mfma_f32_16x16x32_bf16 v[106:109], v[98:101], v[178:181], v[106:109]
	v_mfma_f32_16x16x32_bf16 v[106:109], v[102:105], v[182:185], v[106:109]
	v_mfma_f32_16x16x32_bf16 v[90:93], v[98:101], v[186:189], v[90:93]
	v_mfma_f32_16x16x32_bf16 v[90:93], v[102:105], v[196:199], v[90:93]
	v_mfma_f32_16x16x32_bf16 v[82:85], v[98:101], v[200:203], v[82:85]
	v_mfma_f32_16x16x32_bf16 v[82:85], v[102:105], v[204:207], v[82:85]
	v_mfma_f32_16x16x32_bf16 v[38:41], v[98:101], v[208:211], v[74:77]
	v_mfma_f32_16x16x32_bf16 v[38:41], v[102:105], v[212:215], v[38:41]
	s_setprio 0
	s_setprio 1
	v_mfma_f32_16x16x32_bf16 v[30:33], v[146:149], v[178:181], v[30:33]
	v_mfma_f32_16x16x32_bf16 v[30:33], v[150:153], v[182:185], v[30:33]
	v_mfma_f32_16x16x32_bf16 v[22:25], v[146:149], v[186:189], v[22:25]
	v_mfma_f32_16x16x32_bf16 v[22:25], v[150:153], v[196:199], v[22:25]
	v_mfma_f32_16x16x32_bf16 v[14:17], v[146:149], v[200:203], v[14:17]
	v_mfma_f32_16x16x32_bf16 v[14:17], v[150:153], v[204:207], v[14:17]
	v_mfma_f32_16x16x32_bf16 v[6:9], v[146:149], v[208:211], v[6:9]
	v_mfma_f32_16x16x32_bf16 v[6:9], v[150:153], v[212:215], v[6:9]
	v_mfma_f32_16x16x32_bf16 v[26:29], v[154:157], v[178:181], v[26:29]
	v_mfma_f32_16x16x32_bf16 v[26:29], v[158:161], v[182:185], v[26:29]
	v_mfma_f32_16x16x32_bf16 v[18:21], v[154:157], v[186:189], v[18:21]
	v_mfma_f32_16x16x32_bf16 v[18:21], v[158:161], v[196:199], v[18:21]
	v_mfma_f32_16x16x32_bf16 v[10:13], v[154:157], v[200:203], v[10:13]
	v_mfma_f32_16x16x32_bf16 v[10:13], v[158:161], v[204:207], v[10:13]
	v_mfma_f32_16x16x32_bf16 v[2:5], v[154:157], v[208:211], v[2:5]
	v_mfma_f32_16x16x32_bf16 v[2:5], v[158:161], v[212:215], v[2:5]
	s_setprio 0
	s_barrier
	s_add_i32 s38, 0, 0x18000
	s_add_i32 s39, 0, 0x1c000
	ds_read_b128 v[74:77], v244 offset:32768
	ds_read_b128 v[78:81], v244 offset:33792
	ds_read_b128 v[98:101], v244 offset:34816
	ds_read_b128 v[102:105], v244 offset:35840
	ds_read_b128 v[146:149], v244 offset:49152
	ds_read_b128 v[150:153], v244 offset:50176
	ds_read_b128 v[154:157], v244 offset:51200
	ds_read_b128 v[158:161], v244 offset:52224
	s_add_u32 s4, s10, 0x160000
	s_addc_u32 s5, s11, 0
	s_mov_b32 m0, s18
	ds_read_b128 v[178:181], v194 offset:32768
	ds_read_b128 v[182:185], v194 offset:33792
	ds_read_b128 v[186:189], v194 offset:34816
	ds_read_b128 v[196:199], v194 offset:35840
	ds_read_b128 v[200:203], v194 offset:36864
	ds_read_b128 v[204:207], v194 offset:37888
	ds_read_b128 v[208:211], v194 offset:38912
	ds_read_b128 v[212:215], v194 offset:39936
	s_nop 0
	global_load_lds_dwordx4 v1, s[4:5]
	s_mov_b32 m0, s19
	s_nop 0
	global_load_lds_dwordx4 v164, s[4:5]
	s_waitcnt vmcnt(8)
	s_waitcnt lgkmcnt(0)
	s_barrier
	s_setprio 1
	s_waitcnt lgkmcnt(0)
	v_mfma_f32_16x16x32_bf16 v[142:145], v[74:77], v[178:181], v[142:145]
	v_mfma_f32_16x16x32_bf16 v[142:145], v[78:81], v[182:185], v[142:145]
	v_mfma_f32_16x16x32_bf16 v[134:137], v[74:77], v[186:189], v[134:137]
	v_mfma_f32_16x16x32_bf16 v[134:137], v[78:81], v[196:199], v[134:137]
	v_mfma_f32_16x16x32_bf16 v[126:129], v[74:77], v[200:203], v[126:129]
	v_mfma_f32_16x16x32_bf16 v[126:129], v[78:81], v[204:207], v[126:129]
	v_mfma_f32_16x16x32_bf16 v[118:121], v[74:77], v[208:211], v[118:121]
	v_mfma_f32_16x16x32_bf16 v[118:121], v[78:81], v[212:215], v[118:121]
	v_mfma_f32_16x16x32_bf16 v[138:141], v[98:101], v[178:181], v[138:141]
	v_mfma_f32_16x16x32_bf16 v[138:141], v[102:105], v[182:185], v[138:141]
	v_mfma_f32_16x16x32_bf16 v[130:133], v[98:101], v[186:189], v[130:133]
	v_mfma_f32_16x16x32_bf16 v[130:133], v[102:105], v[196:199], v[130:133]
	v_mfma_f32_16x16x32_bf16 v[122:125], v[98:101], v[200:203], v[122:125]
	v_mfma_f32_16x16x32_bf16 v[122:125], v[102:105], v[204:207], v[122:125]
	v_mfma_f32_16x16x32_bf16 v[114:117], v[98:101], v[208:211], v[114:117]
	v_mfma_f32_16x16x32_bf16 v[114:117], v[102:105], v[212:215], v[114:117]
	s_setprio 0
	s_setprio 1
	v_mfma_f32_16x16x32_bf16 v[70:73], v[146:149], v[178:181], v[70:73]
	v_mfma_f32_16x16x32_bf16 v[70:73], v[150:153], v[182:185], v[70:73]
	v_mfma_f32_16x16x32_bf16 v[62:65], v[146:149], v[186:189], v[62:65]
	v_mfma_f32_16x16x32_bf16 v[62:65], v[150:153], v[196:199], v[62:65]
	v_mfma_f32_16x16x32_bf16 v[54:57], v[146:149], v[200:203], v[54:57]
	v_mfma_f32_16x16x32_bf16 v[54:57], v[150:153], v[204:207], v[54:57]
	v_mfma_f32_16x16x32_bf16 v[46:49], v[146:149], v[208:211], v[46:49]
	v_mfma_f32_16x16x32_bf16 v[46:49], v[150:153], v[212:215], v[46:49]
	v_mfma_f32_16x16x32_bf16 v[66:69], v[154:157], v[178:181], v[66:69]
	v_mfma_f32_16x16x32_bf16 v[66:69], v[158:161], v[182:185], v[66:69]
	v_mfma_f32_16x16x32_bf16 v[58:61], v[154:157], v[186:189], v[58:61]
	v_mfma_f32_16x16x32_bf16 v[58:61], v[158:161], v[196:199], v[58:61]
	v_mfma_f32_16x16x32_bf16 v[50:53], v[154:157], v[200:203], v[50:53]
	v_mfma_f32_16x16x32_bf16 v[50:53], v[158:161], v[204:207], v[50:53]
	v_mfma_f32_16x16x32_bf16 v[42:45], v[154:157], v[208:211], v[42:45]
	v_mfma_f32_16x16x32_bf16 v[42:45], v[158:161], v[212:215], v[42:45]
	s_setprio 0
	s_barrier
; #define PG8_STAGE(bufoff, gbase, voff) do { const char* gb_ = (const char*)(gbase); asm volatile("" : "+s"(gb_)); _Pragma("unroll") for (int _i = 0; _i < 2; ++_i) { unsigned vo_ = (voff)[_i]; asm volatile("" : "+v"(vo_));        \
;         __builtin_amdgcn_global_load_lds((const unsigned*)(gb_ + vo_), (PG8_LAS unsigned*)(lds + (bufoff) + ldsw + _i * 8192), 16, 0, 0); } } while (0)
; #define PG8_LDA(dst, b, h) do { _Pragma("unroll") for (int m = 0; m < 4; ++m) _Pragma("unroll") for (int k = 0; k < 2; ++k) dst[m][k] = *(const PG8_LAS bf16x8*)(lds + PG8_SA(b, h) + aoff + m * 2048 + k * 1024); } while (0)
;     __device__ __forceinline__ void operator()(const f32x4 (&acc)[2][2][4][2], const Unit& u, int wr, int wc, int fr, int fq) const {
;         const int row0 = u.pm * BM + wr * 64 + fr, col0 = u.pn * BM + wc * 32 + 8 * fq, b = (u.pm * BM) / rows_per_batch;
;         const float* g = gate + (size_t)b * gate_bstride + col0;
;         float ssq[2][4];
; #pragma unroll
;         for (int ai = 0; ai < 2; ++ai)
; #pragma unroll
;             for (int m = 0; m < 4; ++m) ssq[ai][m] = 0.f;
;         f32x4 gv[2][2], Gv[2][2];
; #pragma unroll
;         for (int bj = 0; bj < 2; ++bj) { gv[bj][0] = *(const f32x4*)(g + bj * HALF); gv[bj][1] = *(const f32x4*)(g + bj * HALF + 4); Gv[bj][0] = (f32x4){0.f, 0.f, 0.f, 0.f}; Gv[bj][1] = (f32x4){0.f, 0.f, 0.f, 0.f};
;             if (Hn) { const float* sc = scnext + (size_t)b * gate_bstride + col0 + bj * HALF;
;                 Gv[bj][0] = *(const f32x4*)(gnext + col0 + bj * HALF) * (1.0f + *(const f32x4*)(sc)); Gv[bj][1] = *(const f32x4*)(gnext + col0 + bj * HALF + 4) * (1.0f + *(const f32x4*)(sc + 4)); } }
; template <class Epi, class Sched, bool ALIGN_EPI = false, bool SP2 = false>
; __device__ __forceinline__ void gemm_phase(PG8_LAS unsigned char* lds, const Gemm g, const Sched& S, const Epi& E) {
;     ...
;             PG8_LDB(B0, 1, 0); PG8_LDB(B1, 1, 1); PG8_SCHED; PG8_LDA(At, 1, 0); PG8_STAGE(PG8_SA(0, 1), a2 + hstep, voffA);
;             PG8_WAIT_V(8); PG8_WAIT_L(0); PG8_BAR; PG8_MMA(0, 0, At, B0); PG8_MMA(0, 1, At, B1); PG8_BAR; PG8_SCHED;
;             PG8_LDA(At, 1, 1); PG8_STAGE(PG8_SB(1, 0), b3, voffB); PG8_STAGE(PG8_SB(1, 1), b3 + hstep, voffB); PG8_STAGE(PG8_SA(1, 0), a3, voffA);
;             PG8_WAIT_V(8); PG8_WAIT_L(0); PG8_BAR; PG8_MMA(1, 0, At, B0); PG8_MMA(1, 1, At, B1); PG8_BAR; PG8_SCHED;
	s_add_u32 s4, s8, 0x80
	s_addc_u32 s5, s9, 0
	s_add_i32 s10, s38, s15
	ds_read_b128 v[178:181], v194 offset:49152
	ds_read_b128 v[182:185], v194 offset:50176
	ds_read_b128 v[186:189], v194 offset:51200
	ds_read_b128 v[196:199], v194 offset:52224
	ds_read_b128 v[200:203], v194 offset:53248
	ds_read_b128 v[204:207], v194 offset:54272
	ds_read_b128 v[208:211], v194 offset:55296
	ds_read_b128 v[212:215], v194 offset:56320
	s_mov_b32 m0, s10
	s_nop 0
	global_load_lds_dwordx4 v162, s[4:5]
	s_add_i32 m0, s10, 0x2000
	s_nop 0
	global_load_lds_dwordx4 v190, s[4:5]
	s_add_u32 s4, s8, 0x160080
	s_addc_u32 s5, s9, 0
	s_add_i32 s8, s39, s15
	s_mov_b32 m0, s8
	s_nop 0
	global_load_lds_dwordx4 v162, s[4:5]
	s_add_i32 m0, s8, 0x2000
	s_nop 0
	global_load_lds_dwordx4 v190, s[4:5]
	s_mov_b32 m0, s24
	s_nop 0
	global_load_lds_dwordx4 v1, s[6:7]
	s_mov_b32 m0, s25
	s_nop 0
	global_load_lds_dwordx4 v164, s[6:7]
	s_waitcnt vmcnt(8)
	s_waitcnt lgkmcnt(0)
	s_barrier
	s_setprio 1
	s_waitcnt lgkmcnt(0)
	v_mfma_f32_16x16x32_bf16 v[110:113], v[74:77], v[178:181], v[110:113]
	v_mfma_f32_16x16x32_bf16 v[110:113], v[78:81], v[182:185], v[110:113]
	v_mfma_f32_16x16x32_bf16 v[94:97], v[74:77], v[186:189], v[94:97]
	v_mfma_f32_16x16x32_bf16 v[94:97], v[78:81], v[196:199], v[94:97]
	v_mfma_f32_16x16x32_bf16 v[86:89], v[74:77], v[200:203], v[86:89]
	v_mfma_f32_16x16x32_bf16 v[86:89], v[78:81], v[204:207], v[86:89]
	v_mfma_f32_16x16x32_bf16 v[34:37], v[74:77], v[208:211], v[34:37]
	v_mfma_f32_16x16x32_bf16 v[78:81], v[78:81], v[212:215], v[34:37]
	v_mfma_f32_16x16x32_bf16 v[106:109], v[98:101], v[178:181], v[106:109]
	v_mfma_f32_16x16x32_bf16 v[106:109], v[102:105], v[182:185], v[106:109]
	v_mfma_f32_16x16x32_bf16 v[90:93], v[98:101], v[186:189], v[90:93]
	v_mfma_f32_16x16x32_bf16 v[90:93], v[102:105], v[196:199], v[90:93]
	v_mfma_f32_16x16x32_bf16 v[82:85], v[98:101], v[200:203], v[82:85]
	v_mfma_f32_16x16x32_bf16 v[82:85], v[102:105], v[204:207], v[82:85]
	v_mfma_f32_16x16x32_bf16 v[34:37], v[98:101], v[208:211], v[38:41]
	v_mfma_f32_16x16x32_bf16 v[74:77], v[102:105], v[212:215], v[34:37]
	s_setprio 0
	s_setprio 1
	v_mfma_f32_16x16x32_bf16 v[30:33], v[146:149], v[178:181], v[30:33]
	v_mfma_f32_16x16x32_bf16 v[30:33], v[150:153], v[182:185], v[30:33]
	v_mfma_f32_16x16x32_bf16 v[22:25], v[146:149], v[186:189], v[22:25]
	v_mfma_f32_16x16x32_bf16 v[22:25], v[150:153], v[196:199], v[22:25]
	v_mfma_f32_16x16x32_bf16 v[14:17], v[146:149], v[200:203], v[14:17]
	v_mfma_f32_16x16x32_bf16 v[14:17], v[150:153], v[204:207], v[14:17]
	v_mfma_f32_16x16x32_bf16 v[6:9], v[146:149], v[208:211], v[6:9]
	v_mfma_f32_16x16x32_bf16 v[6:9], v[150:153], v[212:215], v[6:9]
	v_mfma_f32_16x16x32_bf16 v[26:29], v[154:157], v[178:181], v[26:29]
	v_mfma_f32_16x16x32_bf16 v[26:29], v[158:161], v[182:185], v[26:29]
	v_mfma_f32_16x16x32_bf16 v[18:21], v[154:157], v[186:189], v[18:21]
	v_mfma_f32_16x16x32_bf16 v[18:21], v[158:161], v[196:199], v[18:21]
	v_mfma_f32_16x16x32_bf16 v[10:13], v[154:157], v[200:203], v[10:13]
	v_mfma_f32_16x16x32_bf16 v[10:13], v[158:161], v[204:207], v[10:13]
	v_mfma_f32_16x16x32_bf16 v[2:5], v[154:157], v[208:211], v[2:5]
	v_mfma_f32_16x16x32_bf16 v[2:5], v[158:161], v[212:215], v[2:5]
	s_setprio 0
	s_barrier
	s_add_i32 s35, s35, 2
	s_add_u32 s31, s31, 0x100
	s_addc_u32 s34, s34, 0
	s_cmpk_gt_u32 s35, 0x55
	s_mov_b64 s[4:5], s[2:3]
	s_cbranch_scc0 .LBB0_707
	s_ashr_i32 s2, s29, 31
	s_lshr_b32 s2, s2, 27
	s_add_i32 s2, s29, s2
	s_ashr_i32 s2, s2, 5
	v_lshl_or_b32 v156, s30, 8, v193
	s_mul_i32 s5, s2, 0xc000
	v_ashrrev_i32_e32 v157, 31, v156
	s_mul_hi_i32 s4, s2, 0xc000
	s_add_u32 s2, s20, s5
	s_addc_u32 s3, s21, s4
	v_lshlrev_b64 v[34:35], 2, v[156:157]
	v_lshl_add_u64 v[38:39], s[2:3], 0, v[34:35]
	global_load_dwordx4 v[98:101], v[38:39], off offset:16
	global_load_dwordx4 v[102:105], v[38:39], off
	s_add_u32 s2, s22, s5
	s_addc_u32 s3, s23, s4
	v_lshl_add_u64 v[148:149], s[2:3], 0, v[34:35]
	v_lshl_add_u64 v[146:147], s[48:49], 0, v[34:35]
	v_mov_b32_e32 v158, 0
	v_cndmask_b32_e64 v34, 0, 1, s[46:47]
	v_cmp_ne_u32_e64 s[2:3], 1, v34
	s_andn2_b64 vcc, exec, s[46:47]
	v_mov_b32_e32 v159, v158
	v_mov_b32_e32 v160, v158
	v_mov_b32_e32 v161, v158
	v_mov_b32_e32 v178, v158
	v_mov_b32_e32 v179, v158
	v_mov_b32_e32 v180, v158
	v_mov_b32_e32 v181, v158
	s_cbranch_vccnz .LBB0_710
	global_load_dwordx4 v[34:37], v[148:149], off
	global_load_dwordx4 v[150:153], v[148:149], off offset:16
	global_load_dwordx4 v[158:161], v[146:147], off
	global_load_dwordx4 v[178:181], v[146:147], off offset:16
	s_waitcnt vmcnt(0)
	v_pk_add_f32 v[36:37], v[36:37], 1.0 op_sel_hi:[1,0]
	v_pk_add_f32 v[34:35], v[34:35], 1.0 op_sel_hi:[1,0]
	v_pk_add_f32 v[40:41], v[152:153], 1.0 op_sel_hi:[1,0]
	v_pk_add_f32 v[150:151], v[150:151], 1.0 op_sel_hi:[1,0]
	v_pk_mul_f32 v[160:161], v[160:161], v[36:37]
	v_pk_mul_f32 v[158:159], v[158:159], v[34:35]
	v_pk_mul_f32 v[180:181], v[180:181], v[40:41]
	v_pk_mul_f32 v[178:179], v[178:179], v[150:151]
